# in-projection epilogue: plain write-back stores instead of non-temporal stores
# baseline (speedup 1.0000x reference)
.Linp_epi:
	s_nop 4
	v_and_b32_e32 v64, 15, v127
	v_bfe_u32 v65, v127, 4, 2
	v_bfe_u32 v66, v127, 6, 1
	v_lshrrev_b32_e32 v67, 7, v127
	s_and_b32 s0, s38, 0x1ff
	v_lshl_add_u32 v68, v66, 6, v64
	v_add_u32_e32 v68, s0, v68
	v_lshlrev_b32_e32 v69, 6, v67
	v_lshl_add_u32 v69, v65, 2, v69
	v_add_u32_e32 v69, s37, v69
	s_lshr_b32 s1, s38, 9
	s_mov_b32 s7, 0x7060302
	s_cmp_lt_u32 s1, 2
	s_cbranch_scc1 .Lie_qk
	s_cmp_eq_u32 s1, 2
	s_cbranch_scc1 .Lie_v
	s_cmp_eq_u32 s1, 3
	s_cbranch_scc1 .Lie_xb
	v_lshlrev_b32_e32 v74, 10, v69
	v_lshl_add_u32 v74, v68, 1, v74
	s_mov_b32 s4, 0x3d372713
	s_mov_b32 s5, 0x3f4c422a
	s_mov_b32 s6, 0x4038aa3b
	v_mov_b32_e32 v80, v74
	v_mul_f32_e32 v88, s4, v0
	v_mul_f32_e32 v89, s4, v4
	v_mul_f32_e32 v90, s4, v8
	v_mul_f32_e32 v91, s4, v12
	v_mul_f32_e32 v88, v88, v0
	v_mul_f32_e32 v89, v89, v4
	v_mul_f32_e32 v90, v90, v8
	v_mul_f32_e32 v91, v91, v12
	v_mul_f32_e32 v88, v88, v0
	v_mul_f32_e32 v89, v89, v4
	v_mul_f32_e32 v90, v90, v8
	v_mul_f32_e32 v91, v91, v12
	v_add_f32_e32 v88, v0, v88
	v_add_f32_e32 v89, v4, v89
	v_add_f32_e32 v90, v8, v90
	v_add_f32_e32 v91, v12, v91
	v_mul_f32_e32 v88, s5, v88
	v_mul_f32_e32 v89, s5, v89
	v_mul_f32_e32 v90, s5, v90
	v_mul_f32_e32 v91, s5, v91
	v_mul_f32_e32 v88, s6, v88
	v_mul_f32_e32 v89, s6, v89
	v_mul_f32_e32 v90, s6, v90
	v_mul_f32_e32 v91, s6, v91
	v_exp_f32_e32 v88, v88
	v_exp_f32_e32 v89, v89
	v_exp_f32_e32 v90, v90
	v_exp_f32_e32 v91, v91
	v_mul_f32_e32 v92, 0.5, v0
	v_mul_f32_e32 v93, 0.5, v4
	v_mul_f32_e32 v94, 0.5, v8
	v_mul_f32_e32 v95, 0.5, v12
	v_add_f32_e32 v88, 1.0, v88
	v_add_f32_e32 v89, 1.0, v89
	v_add_f32_e32 v90, 1.0, v90
	v_add_f32_e32 v91, 1.0, v91
	v_rcp_f32_e32 v88, v88
	v_rcp_f32_e32 v89, v89
	v_rcp_f32_e32 v90, v90
	v_rcp_f32_e32 v91, v91
	s_nop 0
	v_fma_f32 v88, v88, -2.0, 1.0
	v_fma_f32 v89, v89, -2.0, 1.0
	v_fma_f32 v90, v90, -2.0, 1.0
	v_fma_f32 v91, v91, -2.0, 1.0
	v_add_f32_e32 v88, 1.0, v88
	v_add_f32_e32 v89, 1.0, v89
	v_add_f32_e32 v90, 1.0, v90
	v_add_f32_e32 v91, 1.0, v91
	v_mul_f32_e32 v92, v92, v88
	v_mul_f32_e32 v93, v93, v89
	v_mul_f32_e32 v94, v94, v90
	v_mul_f32_e32 v95, v95, v91
	v_bfe_u32 v88, v92, 16, 1
	v_bfe_u32 v89, v93, 16, 1
	v_bfe_u32 v90, v94, 16, 1
	v_bfe_u32 v91, v95, 16, 1
	v_add3_u32 v92, v92, v88, s33
	v_add3_u32 v93, v93, v89, s33
	v_add3_u32 v94, v94, v90, s33
	v_add3_u32 v95, v95, v91, s33
	global_store_short_d16_hi v80, v92, s[24:25] offset:0
	global_store_short_d16_hi v80, v93, s[24:25] offset:32
	global_store_short_d16_hi v80, v94, s[24:25] offset:64
	global_store_short_d16_hi v80, v95, s[24:25] offset:96
	v_add_u32_e32 v80, 0x400, v74
	v_mul_f32_e32 v88, s4, v1
	v_mul_f32_e32 v89, s4, v5
	v_mul_f32_e32 v90, s4, v9
	v_mul_f32_e32 v91, s4, v13
	v_mul_f32_e32 v88, v88, v1
	v_mul_f32_e32 v89, v89, v5
	v_mul_f32_e32 v90, v90, v9
	v_mul_f32_e32 v91, v91, v13
	v_mul_f32_e32 v88, v88, v1
	v_mul_f32_e32 v89, v89, v5
	v_mul_f32_e32 v90, v90, v9
	v_mul_f32_e32 v91, v91, v13
	v_add_f32_e32 v88, v1, v88
	v_add_f32_e32 v89, v5, v89
	v_add_f32_e32 v90, v9, v90
	v_add_f32_e32 v91, v13, v91
	v_mul_f32_e32 v88, s5, v88
	v_mul_f32_e32 v89, s5, v89
	v_mul_f32_e32 v90, s5, v90
	v_mul_f32_e32 v91, s5, v91
	v_mul_f32_e32 v88, s6, v88
	v_mul_f32_e32 v89, s6, v89
	v_mul_f32_e32 v90, s6, v90
	v_mul_f32_e32 v91, s6, v91
	v_exp_f32_e32 v88, v88
	v_exp_f32_e32 v89, v89
	v_exp_f32_e32 v90, v90
	v_exp_f32_e32 v91, v91
	v_mul_f32_e32 v92, 0.5, v1
	v_mul_f32_e32 v93, 0.5, v5
	v_mul_f32_e32 v94, 0.5, v9
	v_mul_f32_e32 v95, 0.5, v13
	v_add_f32_e32 v88, 1.0, v88
	v_add_f32_e32 v89, 1.0, v89
	v_add_f32_e32 v90, 1.0, v90
	v_add_f32_e32 v91, 1.0, v91
	v_rcp_f32_e32 v88, v88
	v_rcp_f32_e32 v89, v89
	v_rcp_f32_e32 v90, v90
	v_rcp_f32_e32 v91, v91
	s_nop 0
	v_fma_f32 v88, v88, -2.0, 1.0
	v_fma_f32 v89, v89, -2.0, 1.0
	v_fma_f32 v90, v90, -2.0, 1.0
	v_fma_f32 v91, v91, -2.0, 1.0
	v_add_f32_e32 v88, 1.0, v88
	v_add_f32_e32 v89, 1.0, v89
	v_add_f32_e32 v90, 1.0, v90
	v_add_f32_e32 v91, 1.0, v91
	v_mul_f32_e32 v92, v92, v88
	v_mul_f32_e32 v93, v93, v89
	v_mul_f32_e32 v94, v94, v90
	v_mul_f32_e32 v95, v95, v91
	v_bfe_u32 v88, v92, 16, 1
	v_bfe_u32 v89, v93, 16, 1
	v_bfe_u32 v90, v94, 16, 1
	v_bfe_u32 v91, v95, 16, 1
	v_add3_u32 v92, v92, v88, s33
	v_add3_u32 v93, v93, v89, s33
	v_add3_u32 v94, v94, v90, s33
	v_add3_u32 v95, v95, v91, s33
	global_store_short_d16_hi v80, v92, s[24:25] offset:0
	global_store_short_d16_hi v80, v93, s[24:25] offset:32
	global_store_short_d16_hi v80, v94, s[24:25] offset:64
	global_store_short_d16_hi v80, v95, s[24:25] offset:96
	v_add_u32_e32 v80, 0x800, v74
	v_mul_f32_e32 v88, s4, v2
	v_mul_f32_e32 v89, s4, v6
	v_mul_f32_e32 v90, s4, v10
	v_mul_f32_e32 v91, s4, v14
	v_mul_f32_e32 v88, v88, v2
	v_mul_f32_e32 v89, v89, v6
	v_mul_f32_e32 v90, v90, v10
	v_mul_f32_e32 v91, v91, v14
	v_mul_f32_e32 v88, v88, v2
	v_mul_f32_e32 v89, v89, v6
	v_mul_f32_e32 v90, v90, v10
	v_mul_f32_e32 v91, v91, v14
	v_add_f32_e32 v88, v2, v88
	v_add_f32_e32 v89, v6, v89
	v_add_f32_e32 v90, v10, v90
	v_add_f32_e32 v91, v14, v91
	v_mul_f32_e32 v88, s5, v88
	v_mul_f32_e32 v89, s5, v89
	v_mul_f32_e32 v90, s5, v90
	v_mul_f32_e32 v91, s5, v91
	v_mul_f32_e32 v88, s6, v88
	v_mul_f32_e32 v89, s6, v89
	v_mul_f32_e32 v90, s6, v90
	v_mul_f32_e32 v91, s6, v91
	v_exp_f32_e32 v88, v88
	v_exp_f32_e32 v89, v89
	v_exp_f32_e32 v90, v90
	v_exp_f32_e32 v91, v91
	v_mul_f32_e32 v92, 0.5, v2
	v_mul_f32_e32 v93, 0.5, v6
	v_mul_f32_e32 v94, 0.5, v10
	v_mul_f32_e32 v95, 0.5, v14
	v_add_f32_e32 v88, 1.0, v88
	v_add_f32_e32 v89, 1.0, v89
	v_add_f32_e32 v90, 1.0, v90
	v_add_f32_e32 v91, 1.0, v91
	v_rcp_f32_e32 v88, v88
	v_rcp_f32_e32 v89, v89
	v_rcp_f32_e32 v90, v90
	v_rcp_f32_e32 v91, v91
	s_nop 0
	v_fma_f32 v88, v88, -2.0, 1.0
	v_fma_f32 v89, v89, -2.0, 1.0
	v_fma_f32 v90, v90, -2.0, 1.0
	v_fma_f32 v91, v91, -2.0, 1.0
	v_add_f32_e32 v88, 1.0, v88
	v_add_f32_e32 v89, 1.0, v89
	v_add_f32_e32 v90, 1.0, v90
	v_add_f32_e32 v91, 1.0, v91
	v_mul_f32_e32 v92, v92, v88
	v_mul_f32_e32 v93, v93, v89
	v_mul_f32_e32 v94, v94, v90
	v_mul_f32_e32 v95, v95, v91
	v_bfe_u32 v88, v92, 16, 1
	v_bfe_u32 v89, v93, 16, 1
	v_bfe_u32 v90, v94, 16, 1
	v_bfe_u32 v91, v95, 16, 1
	v_add3_u32 v92, v92, v88, s33
	v_add3_u32 v93, v93, v89, s33
	v_add3_u32 v94, v94, v90, s33
	v_add3_u32 v95, v95, v91, s33
	global_store_short_d16_hi v80, v92, s[24:25] offset:0
	global_store_short_d16_hi v80, v93, s[24:25] offset:32
	global_store_short_d16_hi v80, v94, s[24:25] offset:64
	global_store_short_d16_hi v80, v95, s[24:25] offset:96
	v_add_u32_e32 v80, 0xc00, v74
	v_mul_f32_e32 v88, s4, v3
	v_mul_f32_e32 v89, s4, v7
	v_mul_f32_e32 v90, s4, v11
	v_mul_f32_e32 v91, s4, v15
	v_mul_f32_e32 v88, v88, v3
	v_mul_f32_e32 v89, v89, v7
	v_mul_f32_e32 v90, v90, v11
	v_mul_f32_e32 v91, v91, v15
	v_mul_f32_e32 v88, v88, v3
	v_mul_f32_e32 v89, v89, v7
	v_mul_f32_e32 v90, v90, v11
	v_mul_f32_e32 v91, v91, v15
	v_add_f32_e32 v88, v3, v88
	v_add_f32_e32 v89, v7, v89
	v_add_f32_e32 v90, v11, v90
	v_add_f32_e32 v91, v15, v91
	v_mul_f32_e32 v88, s5, v88
	v_mul_f32_e32 v89, s5, v89
	v_mul_f32_e32 v90, s5, v90
	v_mul_f32_e32 v91, s5, v91
	v_mul_f32_e32 v88, s6, v88
	v_mul_f32_e32 v89, s6, v89
	v_mul_f32_e32 v90, s6, v90
	v_mul_f32_e32 v91, s6, v91
	v_exp_f32_e32 v88, v88
	v_exp_f32_e32 v89, v89
	v_exp_f32_e32 v90, v90
	v_exp_f32_e32 v91, v91
	v_mul_f32_e32 v92, 0.5, v3
	v_mul_f32_e32 v93, 0.5, v7
	v_mul_f32_e32 v94, 0.5, v11
	v_mul_f32_e32 v95, 0.5, v15
	v_add_f32_e32 v88, 1.0, v88
	v_add_f32_e32 v89, 1.0, v89
	v_add_f32_e32 v90, 1.0, v90
	v_add_f32_e32 v91, 1.0, v91
	v_rcp_f32_e32 v88, v88
	v_rcp_f32_e32 v89, v89
	v_rcp_f32_e32 v90, v90
	v_rcp_f32_e32 v91, v91
	s_nop 0
	v_fma_f32 v88, v88, -2.0, 1.0
	v_fma_f32 v89, v89, -2.0, 1.0
	v_fma_f32 v90, v90, -2.0, 1.0
	v_fma_f32 v91, v91, -2.0, 1.0
	v_add_f32_e32 v88, 1.0, v88
	v_add_f32_e32 v89, 1.0, v89
	v_add_f32_e32 v90, 1.0, v90
	v_add_f32_e32 v91, 1.0, v91
	v_mul_f32_e32 v92, v92, v88
	v_mul_f32_e32 v93, v93, v89
	v_mul_f32_e32 v94, v94, v90
	v_mul_f32_e32 v95, v95, v91
	v_bfe_u32 v88, v92, 16, 1
	v_bfe_u32 v89, v93, 16, 1
	v_bfe_u32 v90, v94, 16, 1
	v_bfe_u32 v91, v95, 16, 1
	v_add3_u32 v92, v92, v88, s33
	v_add3_u32 v93, v93, v89, s33
	v_add3_u32 v94, v94, v90, s33
	v_add3_u32 v95, v95, v91, s33
	global_store_short_d16_hi v80, v92, s[24:25] offset:0
	global_store_short_d16_hi v80, v93, s[24:25] offset:32
	global_store_short_d16_hi v80, v94, s[24:25] offset:64
	global_store_short_d16_hi v80, v95, s[24:25] offset:96
	v_add_u32_e32 v80, 0x4000, v74
	v_mul_f32_e32 v88, s4, v16
	v_mul_f32_e32 v89, s4, v20
	v_mul_f32_e32 v90, s4, v24
	v_mul_f32_e32 v91, s4, v28
	v_mul_f32_e32 v88, v88, v16
	v_mul_f32_e32 v89, v89, v20
	v_mul_f32_e32 v90, v90, v24
	v_mul_f32_e32 v91, v91, v28
	v_mul_f32_e32 v88, v88, v16
	v_mul_f32_e32 v89, v89, v20
	v_mul_f32_e32 v90, v90, v24
	v_mul_f32_e32 v91, v91, v28
	v_add_f32_e32 v88, v16, v88
	v_add_f32_e32 v89, v20, v89
	v_add_f32_e32 v90, v24, v90
	v_add_f32_e32 v91, v28, v91
	v_mul_f32_e32 v88, s5, v88
	v_mul_f32_e32 v89, s5, v89
	v_mul_f32_e32 v90, s5, v90
	v_mul_f32_e32 v91, s5, v91
	v_mul_f32_e32 v88, s6, v88
	v_mul_f32_e32 v89, s6, v89
	v_mul_f32_e32 v90, s6, v90
	v_mul_f32_e32 v91, s6, v91
	v_exp_f32_e32 v88, v88
	v_exp_f32_e32 v89, v89
	v_exp_f32_e32 v90, v90
	v_exp_f32_e32 v91, v91
	v_mul_f32_e32 v92, 0.5, v16
	v_mul_f32_e32 v93, 0.5, v20
	v_mul_f32_e32 v94, 0.5, v24
	v_mul_f32_e32 v95, 0.5, v28
	v_add_f32_e32 v88, 1.0, v88
	v_add_f32_e32 v89, 1.0, v89
	v_add_f32_e32 v90, 1.0, v90
	v_add_f32_e32 v91, 1.0, v91
	v_rcp_f32_e32 v88, v88
	v_rcp_f32_e32 v89, v89
	v_rcp_f32_e32 v90, v90
	v_rcp_f32_e32 v91, v91
	s_nop 0
	v_fma_f32 v88, v88, -2.0, 1.0
	v_fma_f32 v89, v89, -2.0, 1.0
	v_fma_f32 v90, v90, -2.0, 1.0
	v_fma_f32 v91, v91, -2.0, 1.0
	v_add_f32_e32 v88, 1.0, v88
	v_add_f32_e32 v89, 1.0, v89
	v_add_f32_e32 v90, 1.0, v90
	v_add_f32_e32 v91, 1.0, v91
	v_mul_f32_e32 v92, v92, v88
	v_mul_f32_e32 v93, v93, v89
	v_mul_f32_e32 v94, v94, v90
	v_mul_f32_e32 v95, v95, v91
	v_bfe_u32 v88, v92, 16, 1
	v_bfe_u32 v89, v93, 16, 1
	v_bfe_u32 v90, v94, 16, 1
	v_bfe_u32 v91, v95, 16, 1
	v_add3_u32 v92, v92, v88, s33
	v_add3_u32 v93, v93, v89, s33
	v_add3_u32 v94, v94, v90, s33
	v_add3_u32 v95, v95, v91, s33
	global_store_short_d16_hi v80, v92, s[24:25] offset:0
	global_store_short_d16_hi v80, v93, s[24:25] offset:32
	global_store_short_d16_hi v80, v94, s[24:25] offset:64
	global_store_short_d16_hi v80, v95, s[24:25] offset:96
	v_add_u32_e32 v80, 0x4400, v74
	v_mul_f32_e32 v88, s4, v17
	v_mul_f32_e32 v89, s4, v21
	v_mul_f32_e32 v90, s4, v25
	v_mul_f32_e32 v91, s4, v29
	v_mul_f32_e32 v88, v88, v17
	v_mul_f32_e32 v89, v89, v21
	v_mul_f32_e32 v90, v90, v25
	v_mul_f32_e32 v91, v91, v29
	v_mul_f32_e32 v88, v88, v17
	v_mul_f32_e32 v89, v89, v21
	v_mul_f32_e32 v90, v90, v25
	v_mul_f32_e32 v91, v91, v29
	v_add_f32_e32 v88, v17, v88
	v_add_f32_e32 v89, v21, v89
	v_add_f32_e32 v90, v25, v90
	v_add_f32_e32 v91, v29, v91
	v_mul_f32_e32 v88, s5, v88
	v_mul_f32_e32 v89, s5, v89
	v_mul_f32_e32 v90, s5, v90
	v_mul_f32_e32 v91, s5, v91
	v_mul_f32_e32 v88, s6, v88
	v_mul_f32_e32 v89, s6, v89
	v_mul_f32_e32 v90, s6, v90
	v_mul_f32_e32 v91, s6, v91
	v_exp_f32_e32 v88, v88
	v_exp_f32_e32 v89, v89
	v_exp_f32_e32 v90, v90
	v_exp_f32_e32 v91, v91
	v_mul_f32_e32 v92, 0.5, v17
	v_mul_f32_e32 v93, 0.5, v21
	v_mul_f32_e32 v94, 0.5, v25
	v_mul_f32_e32 v95, 0.5, v29
	v_add_f32_e32 v88, 1.0, v88
	v_add_f32_e32 v89, 1.0, v89
	v_add_f32_e32 v90, 1.0, v90
	v_add_f32_e32 v91, 1.0, v91
	v_rcp_f32_e32 v88, v88
	v_rcp_f32_e32 v89, v89
	v_rcp_f32_e32 v90, v90
	v_rcp_f32_e32 v91, v91
	s_nop 0
	v_fma_f32 v88, v88, -2.0, 1.0
	v_fma_f32 v89, v89, -2.0, 1.0
	v_fma_f32 v90, v90, -2.0, 1.0
	v_fma_f32 v91, v91, -2.0, 1.0
	v_add_f32_e32 v88, 1.0, v88
	v_add_f32_e32 v89, 1.0, v89
	v_add_f32_e32 v90, 1.0, v90
	v_add_f32_e32 v91, 1.0, v91
	v_mul_f32_e32 v92, v92, v88
	v_mul_f32_e32 v93, v93, v89
	v_mul_f32_e32 v94, v94, v90
	v_mul_f32_e32 v95, v95, v91
	v_bfe_u32 v88, v92, 16, 1
	v_bfe_u32 v89, v93, 16, 1
	v_bfe_u32 v90, v94, 16, 1
	v_bfe_u32 v91, v95, 16, 1
	v_add3_u32 v92, v92, v88, s33
	v_add3_u32 v93, v93, v89, s33
	v_add3_u32 v94, v94, v90, s33
	v_add3_u32 v95, v95, v91, s33
	global_store_short_d16_hi v80, v92, s[24:25] offset:0
	global_store_short_d16_hi v80, v93, s[24:25] offset:32
	global_store_short_d16_hi v80, v94, s[24:25] offset:64
	global_store_short_d16_hi v80, v95, s[24:25] offset:96
	v_add_u32_e32 v80, 0x4800, v74
	v_mul_f32_e32 v88, s4, v18
	v_mul_f32_e32 v89, s4, v22
	v_mul_f32_e32 v90, s4, v26
	v_mul_f32_e32 v91, s4, v30
	v_mul_f32_e32 v88, v88, v18
	v_mul_f32_e32 v89, v89, v22
	v_mul_f32_e32 v90, v90, v26
	v_mul_f32_e32 v91, v91, v30
	v_mul_f32_e32 v88, v88, v18
	v_mul_f32_e32 v89, v89, v22
	v_mul_f32_e32 v90, v90, v26
	v_mul_f32_e32 v91, v91, v30
	v_add_f32_e32 v88, v18, v88
	v_add_f32_e32 v89, v22, v89
	v_add_f32_e32 v90, v26, v90
	v_add_f32_e32 v91, v30, v91
	v_mul_f32_e32 v88, s5, v88
	v_mul_f32_e32 v89, s5, v89
	v_mul_f32_e32 v90, s5, v90
	v_mul_f32_e32 v91, s5, v91
	v_mul_f32_e32 v88, s6, v88
	v_mul_f32_e32 v89, s6, v89
	v_mul_f32_e32 v90, s6, v90
	v_mul_f32_e32 v91, s6, v91
	v_exp_f32_e32 v88, v88
	v_exp_f32_e32 v89, v89
	v_exp_f32_e32 v90, v90
	v_exp_f32_e32 v91, v91
	v_mul_f32_e32 v92, 0.5, v18
	v_mul_f32_e32 v93, 0.5, v22
	v_mul_f32_e32 v94, 0.5, v26
	v_mul_f32_e32 v95, 0.5, v30
	v_add_f32_e32 v88, 1.0, v88
	v_add_f32_e32 v89, 1.0, v89
	v_add_f32_e32 v90, 1.0, v90
	v_add_f32_e32 v91, 1.0, v91
	v_rcp_f32_e32 v88, v88
	v_rcp_f32_e32 v89, v89
	v_rcp_f32_e32 v90, v90
	v_rcp_f32_e32 v91, v91
	s_nop 0
	v_fma_f32 v88, v88, -2.0, 1.0
	v_fma_f32 v89, v89, -2.0, 1.0
	v_fma_f32 v90, v90, -2.0, 1.0
	v_fma_f32 v91, v91, -2.0, 1.0
	v_add_f32_e32 v88, 1.0, v88
	v_add_f32_e32 v89, 1.0, v89
	v_add_f32_e32 v90, 1.0, v90
	v_add_f32_e32 v91, 1.0, v91
	v_mul_f32_e32 v92, v92, v88
	v_mul_f32_e32 v93, v93, v89
	v_mul_f32_e32 v94, v94, v90
	v_mul_f32_e32 v95, v95, v91
	v_bfe_u32 v88, v92, 16, 1
	v_bfe_u32 v89, v93, 16, 1
	v_bfe_u32 v90, v94, 16, 1
	v_bfe_u32 v91, v95, 16, 1
	v_add3_u32 v92, v92, v88, s33
	v_add3_u32 v93, v93, v89, s33
	v_add3_u32 v94, v94, v90, s33
	v_add3_u32 v95, v95, v91, s33
	global_store_short_d16_hi v80, v92, s[24:25] offset:0
	global_store_short_d16_hi v80, v93, s[24:25] offset:32
	global_store_short_d16_hi v80, v94, s[24:25] offset:64
	global_store_short_d16_hi v80, v95, s[24:25] offset:96
	v_add_u32_e32 v80, 0x4c00, v74
	v_mul_f32_e32 v88, s4, v19
	v_mul_f32_e32 v89, s4, v23
	v_mul_f32_e32 v90, s4, v27
	v_mul_f32_e32 v91, s4, v31
	v_mul_f32_e32 v88, v88, v19
	v_mul_f32_e32 v89, v89, v23
	v_mul_f32_e32 v90, v90, v27
	v_mul_f32_e32 v91, v91, v31
	v_mul_f32_e32 v88, v88, v19
	v_mul_f32_e32 v89, v89, v23
	v_mul_f32_e32 v90, v90, v27
	v_mul_f32_e32 v91, v91, v31
	v_add_f32_e32 v88, v19, v88
	v_add_f32_e32 v89, v23, v89
	v_add_f32_e32 v90, v27, v90
	v_add_f32_e32 v91, v31, v91
	v_mul_f32_e32 v88, s5, v88
	v_mul_f32_e32 v89, s5, v89
	v_mul_f32_e32 v90, s5, v90
	v_mul_f32_e32 v91, s5, v91
	v_mul_f32_e32 v88, s6, v88
	v_mul_f32_e32 v89, s6, v89
	v_mul_f32_e32 v90, s6, v90
	v_mul_f32_e32 v91, s6, v91
	v_exp_f32_e32 v88, v88
	v_exp_f32_e32 v89, v89
	v_exp_f32_e32 v90, v90
	v_exp_f32_e32 v91, v91
	v_mul_f32_e32 v92, 0.5, v19
	v_mul_f32_e32 v93, 0.5, v23
	v_mul_f32_e32 v94, 0.5, v27
	v_mul_f32_e32 v95, 0.5, v31
	v_add_f32_e32 v88, 1.0, v88
	v_add_f32_e32 v89, 1.0, v89
	v_add_f32_e32 v90, 1.0, v90
	v_add_f32_e32 v91, 1.0, v91
	v_rcp_f32_e32 v88, v88
	v_rcp_f32_e32 v89, v89
	v_rcp_f32_e32 v90, v90
	v_rcp_f32_e32 v91, v91
	s_nop 0
	v_fma_f32 v88, v88, -2.0, 1.0
	v_fma_f32 v89, v89, -2.0, 1.0
	v_fma_f32 v90, v90, -2.0, 1.0
	v_fma_f32 v91, v91, -2.0, 1.0
	v_add_f32_e32 v88, 1.0, v88
	v_add_f32_e32 v89, 1.0, v89
	v_add_f32_e32 v90, 1.0, v90
	v_add_f32_e32 v91, 1.0, v91
	v_mul_f32_e32 v92, v92, v88
	v_mul_f32_e32 v93, v93, v89
	v_mul_f32_e32 v94, v94, v90
	v_mul_f32_e32 v95, v95, v91
	v_bfe_u32 v88, v92, 16, 1
	v_bfe_u32 v89, v93, 16, 1
	v_bfe_u32 v90, v94, 16, 1
	v_bfe_u32 v91, v95, 16, 1
	v_add3_u32 v92, v92, v88, s33
	v_add3_u32 v93, v93, v89, s33
	v_add3_u32 v94, v94, v90, s33
	v_add3_u32 v95, v95, v91, s33
	global_store_short_d16_hi v80, v92, s[24:25] offset:0
	global_store_short_d16_hi v80, v93, s[24:25] offset:32
	global_store_short_d16_hi v80, v94, s[24:25] offset:64
	global_store_short_d16_hi v80, v95, s[24:25] offset:96
	v_add_u32_e32 v80, 0x8000, v74
	v_mul_f32_e32 v88, s4, v32
	v_mul_f32_e32 v89, s4, v36
	v_mul_f32_e32 v90, s4, v40
	v_mul_f32_e32 v91, s4, v44
	v_mul_f32_e32 v88, v88, v32
	v_mul_f32_e32 v89, v89, v36
	v_mul_f32_e32 v90, v90, v40
	v_mul_f32_e32 v91, v91, v44
	v_mul_f32_e32 v88, v88, v32
	v_mul_f32_e32 v89, v89, v36
	v_mul_f32_e32 v90, v90, v40
	v_mul_f32_e32 v91, v91, v44
	v_add_f32_e32 v88, v32, v88
	v_add_f32_e32 v89, v36, v89
	v_add_f32_e32 v90, v40, v90
	v_add_f32_e32 v91, v44, v91
	v_mul_f32_e32 v88, s5, v88
	v_mul_f32_e32 v89, s5, v89
	v_mul_f32_e32 v90, s5, v90
	v_mul_f32_e32 v91, s5, v91
	v_mul_f32_e32 v88, s6, v88
	v_mul_f32_e32 v89, s6, v89
	v_mul_f32_e32 v90, s6, v90
	v_mul_f32_e32 v91, s6, v91
	v_exp_f32_e32 v88, v88
	v_exp_f32_e32 v89, v89
	v_exp_f32_e32 v90, v90
	v_exp_f32_e32 v91, v91
	v_mul_f32_e32 v92, 0.5, v32
	v_mul_f32_e32 v93, 0.5, v36
	v_mul_f32_e32 v94, 0.5, v40
	v_mul_f32_e32 v95, 0.5, v44
	v_add_f32_e32 v88, 1.0, v88
	v_add_f32_e32 v89, 1.0, v89
	v_add_f32_e32 v90, 1.0, v90
	v_add_f32_e32 v91, 1.0, v91
	v_rcp_f32_e32 v88, v88
	v_rcp_f32_e32 v89, v89
	v_rcp_f32_e32 v90, v90
	v_rcp_f32_e32 v91, v91
	s_nop 0
	v_fma_f32 v88, v88, -2.0, 1.0
	v_fma_f32 v89, v89, -2.0, 1.0
	v_fma_f32 v90, v90, -2.0, 1.0
	v_fma_f32 v91, v91, -2.0, 1.0
	v_add_f32_e32 v88, 1.0, v88
	v_add_f32_e32 v89, 1.0, v89
	v_add_f32_e32 v90, 1.0, v90
	v_add_f32_e32 v91, 1.0, v91
	v_mul_f32_e32 v92, v92, v88
	v_mul_f32_e32 v93, v93, v89
	v_mul_f32_e32 v94, v94, v90
	v_mul_f32_e32 v95, v95, v91
	v_bfe_u32 v88, v92, 16, 1
	v_bfe_u32 v89, v93, 16, 1
	v_bfe_u32 v90, v94, 16, 1
	v_bfe_u32 v91, v95, 16, 1
	v_add3_u32 v92, v92, v88, s33
	v_add3_u32 v93, v93, v89, s33
	v_add3_u32 v94, v94, v90, s33
	v_add3_u32 v95, v95, v91, s33
	global_store_short_d16_hi v80, v92, s[24:25] offset:0
	global_store_short_d16_hi v80, v93, s[24:25] offset:32
	global_store_short_d16_hi v80, v94, s[24:25] offset:64
	global_store_short_d16_hi v80, v95, s[24:25] offset:96
	v_add_u32_e32 v80, 0x8400, v74
	v_mul_f32_e32 v88, s4, v33
	v_mul_f32_e32 v89, s4, v37
	v_mul_f32_e32 v90, s4, v41
	v_mul_f32_e32 v91, s4, v45
	v_mul_f32_e32 v88, v88, v33
	v_mul_f32_e32 v89, v89, v37
	v_mul_f32_e32 v90, v90, v41
	v_mul_f32_e32 v91, v91, v45
	v_mul_f32_e32 v88, v88, v33
	v_mul_f32_e32 v89, v89, v37
	v_mul_f32_e32 v90, v90, v41
	v_mul_f32_e32 v91, v91, v45
	v_add_f32_e32 v88, v33, v88
	v_add_f32_e32 v89, v37, v89
	v_add_f32_e32 v90, v41, v90
	v_add_f32_e32 v91, v45, v91
	v_mul_f32_e32 v88, s5, v88
	v_mul_f32_e32 v89, s5, v89
	v_mul_f32_e32 v90, s5, v90
	v_mul_f32_e32 v91, s5, v91
	v_mul_f32_e32 v88, s6, v88
	v_mul_f32_e32 v89, s6, v89
	v_mul_f32_e32 v90, s6, v90
	v_mul_f32_e32 v91, s6, v91
	v_exp_f32_e32 v88, v88
	v_exp_f32_e32 v89, v89
	v_exp_f32_e32 v90, v90
	v_exp_f32_e32 v91, v91
	v_mul_f32_e32 v92, 0.5, v33
	v_mul_f32_e32 v93, 0.5, v37
	v_mul_f32_e32 v94, 0.5, v41
	v_mul_f32_e32 v95, 0.5, v45
	v_add_f32_e32 v88, 1.0, v88
	v_add_f32_e32 v89, 1.0, v89
	v_add_f32_e32 v90, 1.0, v90
	v_add_f32_e32 v91, 1.0, v91
	v_rcp_f32_e32 v88, v88
	v_rcp_f32_e32 v89, v89
	v_rcp_f32_e32 v90, v90
	v_rcp_f32_e32 v91, v91
	s_nop 0
	v_fma_f32 v88, v88, -2.0, 1.0
	v_fma_f32 v89, v89, -2.0, 1.0
	v_fma_f32 v90, v90, -2.0, 1.0
	v_fma_f32 v91, v91, -2.0, 1.0
	v_add_f32_e32 v88, 1.0, v88
	v_add_f32_e32 v89, 1.0, v89
	v_add_f32_e32 v90, 1.0, v90
	v_add_f32_e32 v91, 1.0, v91
	v_mul_f32_e32 v92, v92, v88
	v_mul_f32_e32 v93, v93, v89
	v_mul_f32_e32 v94, v94, v90
	v_mul_f32_e32 v95, v95, v91
	v_bfe_u32 v88, v92, 16, 1
	v_bfe_u32 v89, v93, 16, 1
	v_bfe_u32 v90, v94, 16, 1
	v_bfe_u32 v91, v95, 16, 1
	v_add3_u32 v92, v92, v88, s33
	v_add3_u32 v93, v93, v89, s33
	v_add3_u32 v94, v94, v90, s33
	v_add3_u32 v95, v95, v91, s33
	global_store_short_d16_hi v80, v92, s[24:25] offset:0
	global_store_short_d16_hi v80, v93, s[24:25] offset:32
	global_store_short_d16_hi v80, v94, s[24:25] offset:64
	global_store_short_d16_hi v80, v95, s[24:25] offset:96
	v_add_u32_e32 v80, 0x8800, v74
	v_mul_f32_e32 v88, s4, v34
	v_mul_f32_e32 v89, s4, v38
	v_mul_f32_e32 v90, s4, v42
	v_mul_f32_e32 v91, s4, v46
	v_mul_f32_e32 v88, v88, v34
	v_mul_f32_e32 v89, v89, v38
	v_mul_f32_e32 v90, v90, v42
	v_mul_f32_e32 v91, v91, v46
	v_mul_f32_e32 v88, v88, v34
	v_mul_f32_e32 v89, v89, v38
	v_mul_f32_e32 v90, v90, v42
	v_mul_f32_e32 v91, v91, v46
	v_add_f32_e32 v88, v34, v88
	v_add_f32_e32 v89, v38, v89
	v_add_f32_e32 v90, v42, v90
	v_add_f32_e32 v91, v46, v91
	v_mul_f32_e32 v88, s5, v88
	v_mul_f32_e32 v89, s5, v89
	v_mul_f32_e32 v90, s5, v90
	v_mul_f32_e32 v91, s5, v91
	v_mul_f32_e32 v88, s6, v88
	v_mul_f32_e32 v89, s6, v89
	v_mul_f32_e32 v90, s6, v90
	v_mul_f32_e32 v91, s6, v91
	v_exp_f32_e32 v88, v88
	v_exp_f32_e32 v89, v89
	v_exp_f32_e32 v90, v90
	v_exp_f32_e32 v91, v91
	v_mul_f32_e32 v92, 0.5, v34
	v_mul_f32_e32 v93, 0.5, v38
	v_mul_f32_e32 v94, 0.5, v42
	v_mul_f32_e32 v95, 0.5, v46
	v_add_f32_e32 v88, 1.0, v88
	v_add_f32_e32 v89, 1.0, v89
	v_add_f32_e32 v90, 1.0, v90
	v_add_f32_e32 v91, 1.0, v91
	v_rcp_f32_e32 v88, v88
	v_rcp_f32_e32 v89, v89
	v_rcp_f32_e32 v90, v90
	v_rcp_f32_e32 v91, v91
	s_nop 0
	v_fma_f32 v88, v88, -2.0, 1.0
	v_fma_f32 v89, v89, -2.0, 1.0
	v_fma_f32 v90, v90, -2.0, 1.0
	v_fma_f32 v91, v91, -2.0, 1.0
	v_add_f32_e32 v88, 1.0, v88
	v_add_f32_e32 v89, 1.0, v89
	v_add_f32_e32 v90, 1.0, v90
	v_add_f32_e32 v91, 1.0, v91
	v_mul_f32_e32 v92, v92, v88
	v_mul_f32_e32 v93, v93, v89
	v_mul_f32_e32 v94, v94, v90
	v_mul_f32_e32 v95, v95, v91
	v_bfe_u32 v88, v92, 16, 1
	v_bfe_u32 v89, v93, 16, 1
	v_bfe_u32 v90, v94, 16, 1
	v_bfe_u32 v91, v95, 16, 1
	v_add3_u32 v92, v92, v88, s33
	v_add3_u32 v93, v93, v89, s33
	v_add3_u32 v94, v94, v90, s33
	v_add3_u32 v95, v95, v91, s33
	global_store_short_d16_hi v80, v92, s[24:25] offset:0
	global_store_short_d16_hi v80, v93, s[24:25] offset:32
	global_store_short_d16_hi v80, v94, s[24:25] offset:64
	global_store_short_d16_hi v80, v95, s[24:25] offset:96
	v_add_u32_e32 v80, 0x8c00, v74
	v_mul_f32_e32 v88, s4, v35
	v_mul_f32_e32 v89, s4, v39
	v_mul_f32_e32 v90, s4, v43
	v_mul_f32_e32 v91, s4, v47
	v_mul_f32_e32 v88, v88, v35
	v_mul_f32_e32 v89, v89, v39
	v_mul_f32_e32 v90, v90, v43
	v_mul_f32_e32 v91, v91, v47
	v_mul_f32_e32 v88, v88, v35
	v_mul_f32_e32 v89, v89, v39
	v_mul_f32_e32 v90, v90, v43
	v_mul_f32_e32 v91, v91, v47
	v_add_f32_e32 v88, v35, v88
	v_add_f32_e32 v89, v39, v89
	v_add_f32_e32 v90, v43, v90
	v_add_f32_e32 v91, v47, v91
	v_mul_f32_e32 v88, s5, v88
	v_mul_f32_e32 v89, s5, v89
	v_mul_f32_e32 v90, s5, v90
	v_mul_f32_e32 v91, s5, v91
	v_mul_f32_e32 v88, s6, v88
	v_mul_f32_e32 v89, s6, v89
	v_mul_f32_e32 v90, s6, v90
	v_mul_f32_e32 v91, s6, v91
	v_exp_f32_e32 v88, v88
	v_exp_f32_e32 v89, v89
	v_exp_f32_e32 v90, v90
	v_exp_f32_e32 v91, v91
	v_mul_f32_e32 v92, 0.5, v35
	v_mul_f32_e32 v93, 0.5, v39
	v_mul_f32_e32 v94, 0.5, v43
	v_mul_f32_e32 v95, 0.5, v47
	v_add_f32_e32 v88, 1.0, v88
	v_add_f32_e32 v89, 1.0, v89
	v_add_f32_e32 v90, 1.0, v90
	v_add_f32_e32 v91, 1.0, v91
	v_rcp_f32_e32 v88, v88
	v_rcp_f32_e32 v89, v89
	v_rcp_f32_e32 v90, v90
	v_rcp_f32_e32 v91, v91
	s_nop 0
	v_fma_f32 v88, v88, -2.0, 1.0
	v_fma_f32 v89, v89, -2.0, 1.0
	v_fma_f32 v90, v90, -2.0, 1.0
	v_fma_f32 v91, v91, -2.0, 1.0
	v_add_f32_e32 v88, 1.0, v88
	v_add_f32_e32 v89, 1.0, v89
	v_add_f32_e32 v90, 1.0, v90
	v_add_f32_e32 v91, 1.0, v91
	v_mul_f32_e32 v92, v92, v88
	v_mul_f32_e32 v93, v93, v89
	v_mul_f32_e32 v94, v94, v90
	v_mul_f32_e32 v95, v95, v91
	v_bfe_u32 v88, v92, 16, 1
	v_bfe_u32 v89, v93, 16, 1
	v_bfe_u32 v90, v94, 16, 1
	v_bfe_u32 v91, v95, 16, 1
	v_add3_u32 v92, v92, v88, s33
	v_add3_u32 v93, v93, v89, s33
	v_add3_u32 v94, v94, v90, s33
	v_add3_u32 v95, v95, v91, s33
	global_store_short_d16_hi v80, v92, s[24:25] offset:0
	global_store_short_d16_hi v80, v93, s[24:25] offset:32
	global_store_short_d16_hi v80, v94, s[24:25] offset:64
	global_store_short_d16_hi v80, v95, s[24:25] offset:96
	v_add_u32_e32 v80, 0xc000, v74
	v_mul_f32_e32 v88, s4, v48
	v_mul_f32_e32 v89, s4, v52
	v_mul_f32_e32 v90, s4, v56
	v_mul_f32_e32 v91, s4, v60
	v_mul_f32_e32 v88, v88, v48
	v_mul_f32_e32 v89, v89, v52
	v_mul_f32_e32 v90, v90, v56
	v_mul_f32_e32 v91, v91, v60
	v_mul_f32_e32 v88, v88, v48
	v_mul_f32_e32 v89, v89, v52
	v_mul_f32_e32 v90, v90, v56
	v_mul_f32_e32 v91, v91, v60
	v_add_f32_e32 v88, v48, v88
	v_add_f32_e32 v89, v52, v89
	v_add_f32_e32 v90, v56, v90
	v_add_f32_e32 v91, v60, v91
	v_mul_f32_e32 v88, s5, v88
	v_mul_f32_e32 v89, s5, v89
	v_mul_f32_e32 v90, s5, v90
	v_mul_f32_e32 v91, s5, v91
	v_mul_f32_e32 v88, s6, v88
	v_mul_f32_e32 v89, s6, v89
	v_mul_f32_e32 v90, s6, v90
	v_mul_f32_e32 v91, s6, v91
	v_exp_f32_e32 v88, v88
	v_exp_f32_e32 v89, v89
	v_exp_f32_e32 v90, v90
	v_exp_f32_e32 v91, v91
	v_mul_f32_e32 v92, 0.5, v48
	v_mul_f32_e32 v93, 0.5, v52
	v_mul_f32_e32 v94, 0.5, v56
	v_mul_f32_e32 v95, 0.5, v60
	v_add_f32_e32 v88, 1.0, v88
	v_add_f32_e32 v89, 1.0, v89
	v_add_f32_e32 v90, 1.0, v90
	v_add_f32_e32 v91, 1.0, v91
	v_rcp_f32_e32 v88, v88
	v_rcp_f32_e32 v89, v89
	v_rcp_f32_e32 v90, v90
	v_rcp_f32_e32 v91, v91
	s_nop 0
	v_fma_f32 v88, v88, -2.0, 1.0
	v_fma_f32 v89, v89, -2.0, 1.0
	v_fma_f32 v90, v90, -2.0, 1.0
	v_fma_f32 v91, v91, -2.0, 1.0
	v_add_f32_e32 v88, 1.0, v88
	v_add_f32_e32 v89, 1.0, v89
	v_add_f32_e32 v90, 1.0, v90
	v_add_f32_e32 v91, 1.0, v91
	v_mul_f32_e32 v92, v92, v88
	v_mul_f32_e32 v93, v93, v89
	v_mul_f32_e32 v94, v94, v90
	v_mul_f32_e32 v95, v95, v91
	v_bfe_u32 v88, v92, 16, 1
	v_bfe_u32 v89, v93, 16, 1
	v_bfe_u32 v90, v94, 16, 1
	v_bfe_u32 v91, v95, 16, 1
	v_add3_u32 v92, v92, v88, s33
	v_add3_u32 v93, v93, v89, s33
	v_add3_u32 v94, v94, v90, s33
	v_add3_u32 v95, v95, v91, s33
	global_store_short_d16_hi v80, v92, s[24:25] offset:0
	global_store_short_d16_hi v80, v93, s[24:25] offset:32
	global_store_short_d16_hi v80, v94, s[24:25] offset:64
	global_store_short_d16_hi v80, v95, s[24:25] offset:96
	v_add_u32_e32 v80, 0xc400, v74
	v_mul_f32_e32 v88, s4, v49
	v_mul_f32_e32 v89, s4, v53
	v_mul_f32_e32 v90, s4, v57
	v_mul_f32_e32 v91, s4, v61
	v_mul_f32_e32 v88, v88, v49
	v_mul_f32_e32 v89, v89, v53
	v_mul_f32_e32 v90, v90, v57
	v_mul_f32_e32 v91, v91, v61
	v_mul_f32_e32 v88, v88, v49
	v_mul_f32_e32 v89, v89, v53
	v_mul_f32_e32 v90, v90, v57
	v_mul_f32_e32 v91, v91, v61
	v_add_f32_e32 v88, v49, v88
	v_add_f32_e32 v89, v53, v89
	v_add_f32_e32 v90, v57, v90
	v_add_f32_e32 v91, v61, v91
	v_mul_f32_e32 v88, s5, v88
	v_mul_f32_e32 v89, s5, v89
	v_mul_f32_e32 v90, s5, v90
	v_mul_f32_e32 v91, s5, v91
	v_mul_f32_e32 v88, s6, v88
	v_mul_f32_e32 v89, s6, v89
	v_mul_f32_e32 v90, s6, v90
	v_mul_f32_e32 v91, s6, v91
	v_exp_f32_e32 v88, v88
	v_exp_f32_e32 v89, v89
	v_exp_f32_e32 v90, v90
	v_exp_f32_e32 v91, v91
	v_mul_f32_e32 v92, 0.5, v49
	v_mul_f32_e32 v93, 0.5, v53
	v_mul_f32_e32 v94, 0.5, v57
	v_mul_f32_e32 v95, 0.5, v61
	v_add_f32_e32 v88, 1.0, v88
	v_add_f32_e32 v89, 1.0, v89
	v_add_f32_e32 v90, 1.0, v90
	v_add_f32_e32 v91, 1.0, v91
	v_rcp_f32_e32 v88, v88
	v_rcp_f32_e32 v89, v89
	v_rcp_f32_e32 v90, v90
	v_rcp_f32_e32 v91, v91
	s_nop 0
	v_fma_f32 v88, v88, -2.0, 1.0
	v_fma_f32 v89, v89, -2.0, 1.0
	v_fma_f32 v90, v90, -2.0, 1.0
	v_fma_f32 v91, v91, -2.0, 1.0
	v_add_f32_e32 v88, 1.0, v88
	v_add_f32_e32 v89, 1.0, v89
	v_add_f32_e32 v90, 1.0, v90
	v_add_f32_e32 v91, 1.0, v91
	v_mul_f32_e32 v92, v92, v88
	v_mul_f32_e32 v93, v93, v89
	v_mul_f32_e32 v94, v94, v90
	v_mul_f32_e32 v95, v95, v91
	v_bfe_u32 v88, v92, 16, 1
	v_bfe_u32 v89, v93, 16, 1
	v_bfe_u32 v90, v94, 16, 1
	v_bfe_u32 v91, v95, 16, 1
	v_add3_u32 v92, v92, v88, s33
	v_add3_u32 v93, v93, v89, s33
	v_add3_u32 v94, v94, v90, s33
	v_add3_u32 v95, v95, v91, s33
	global_store_short_d16_hi v80, v92, s[24:25] offset:0
	global_store_short_d16_hi v80, v93, s[24:25] offset:32
	global_store_short_d16_hi v80, v94, s[24:25] offset:64
	global_store_short_d16_hi v80, v95, s[24:25] offset:96
	v_add_u32_e32 v80, 0xc800, v74
	v_mul_f32_e32 v88, s4, v50
	v_mul_f32_e32 v89, s4, v54
	v_mul_f32_e32 v90, s4, v58
	v_mul_f32_e32 v91, s4, v62
	v_mul_f32_e32 v88, v88, v50
	v_mul_f32_e32 v89, v89, v54
	v_mul_f32_e32 v90, v90, v58
	v_mul_f32_e32 v91, v91, v62
	v_mul_f32_e32 v88, v88, v50
	v_mul_f32_e32 v89, v89, v54
	v_mul_f32_e32 v90, v90, v58
	v_mul_f32_e32 v91, v91, v62
	v_add_f32_e32 v88, v50, v88
	v_add_f32_e32 v89, v54, v89
	v_add_f32_e32 v90, v58, v90
	v_add_f32_e32 v91, v62, v91
	v_mul_f32_e32 v88, s5, v88
	v_mul_f32_e32 v89, s5, v89
	v_mul_f32_e32 v90, s5, v90
	v_mul_f32_e32 v91, s5, v91
	v_mul_f32_e32 v88, s6, v88
	v_mul_f32_e32 v89, s6, v89
	v_mul_f32_e32 v90, s6, v90
	v_mul_f32_e32 v91, s6, v91
	v_exp_f32_e32 v88, v88
	v_exp_f32_e32 v89, v89
	v_exp_f32_e32 v90, v90
	v_exp_f32_e32 v91, v91
	v_mul_f32_e32 v92, 0.5, v50
	v_mul_f32_e32 v93, 0.5, v54
	v_mul_f32_e32 v94, 0.5, v58
	v_mul_f32_e32 v95, 0.5, v62
	v_add_f32_e32 v88, 1.0, v88
	v_add_f32_e32 v89, 1.0, v89
	v_add_f32_e32 v90, 1.0, v90
	v_add_f32_e32 v91, 1.0, v91
	v_rcp_f32_e32 v88, v88
	v_rcp_f32_e32 v89, v89
	v_rcp_f32_e32 v90, v90
	v_rcp_f32_e32 v91, v91
	s_nop 0
	v_fma_f32 v88, v88, -2.0, 1.0
	v_fma_f32 v89, v89, -2.0, 1.0
	v_fma_f32 v90, v90, -2.0, 1.0
	v_fma_f32 v91, v91, -2.0, 1.0
	v_add_f32_e32 v88, 1.0, v88
	v_add_f32_e32 v89, 1.0, v89
	v_add_f32_e32 v90, 1.0, v90
	v_add_f32_e32 v91, 1.0, v91
	v_mul_f32_e32 v92, v92, v88
	v_mul_f32_e32 v93, v93, v89
	v_mul_f32_e32 v94, v94, v90
	v_mul_f32_e32 v95, v95, v91
	v_bfe_u32 v88, v92, 16, 1
	v_bfe_u32 v89, v93, 16, 1
	v_bfe_u32 v90, v94, 16, 1
	v_bfe_u32 v91, v95, 16, 1
	v_add3_u32 v92, v92, v88, s33
	v_add3_u32 v93, v93, v89, s33
	v_add3_u32 v94, v94, v90, s33
	v_add3_u32 v95, v95, v91, s33
	global_store_short_d16_hi v80, v92, s[24:25] offset:0
	global_store_short_d16_hi v80, v93, s[24:25] offset:32
	global_store_short_d16_hi v80, v94, s[24:25] offset:64
	global_store_short_d16_hi v80, v95, s[24:25] offset:96
	v_add_u32_e32 v80, 0xcc00, v74
	v_mul_f32_e32 v88, s4, v51
	v_mul_f32_e32 v89, s4, v55
	v_mul_f32_e32 v90, s4, v59
	v_mul_f32_e32 v91, s4, v63
	v_mul_f32_e32 v88, v88, v51
	v_mul_f32_e32 v89, v89, v55
	v_mul_f32_e32 v90, v90, v59
	v_mul_f32_e32 v91, v91, v63
	v_mul_f32_e32 v88, v88, v51
	v_mul_f32_e32 v89, v89, v55
	v_mul_f32_e32 v90, v90, v59
	v_mul_f32_e32 v91, v91, v63
	v_add_f32_e32 v88, v51, v88
	v_add_f32_e32 v89, v55, v89
	v_add_f32_e32 v90, v59, v90
	v_add_f32_e32 v91, v63, v91
	v_mul_f32_e32 v88, s5, v88
	v_mul_f32_e32 v89, s5, v89
	v_mul_f32_e32 v90, s5, v90
	v_mul_f32_e32 v91, s5, v91
	v_mul_f32_e32 v88, s6, v88
	v_mul_f32_e32 v89, s6, v89
	v_mul_f32_e32 v90, s6, v90
	v_mul_f32_e32 v91, s6, v91
	v_exp_f32_e32 v88, v88
	v_exp_f32_e32 v89, v89
	v_exp_f32_e32 v90, v90
	v_exp_f32_e32 v91, v91
	v_mul_f32_e32 v92, 0.5, v51
	v_mul_f32_e32 v93, 0.5, v55
	v_mul_f32_e32 v94, 0.5, v59
	v_mul_f32_e32 v95, 0.5, v63
	v_add_f32_e32 v88, 1.0, v88
	v_add_f32_e32 v89, 1.0, v89
	v_add_f32_e32 v90, 1.0, v90
	v_add_f32_e32 v91, 1.0, v91
	v_rcp_f32_e32 v88, v88
	v_rcp_f32_e32 v89, v89
	v_rcp_f32_e32 v90, v90
	v_rcp_f32_e32 v91, v91
	s_nop 0
	v_fma_f32 v88, v88, -2.0, 1.0
	v_fma_f32 v89, v89, -2.0, 1.0
	v_fma_f32 v90, v90, -2.0, 1.0
	v_fma_f32 v91, v91, -2.0, 1.0
	v_add_f32_e32 v88, 1.0, v88
	v_add_f32_e32 v89, 1.0, v89
	v_add_f32_e32 v90, 1.0, v90
	v_add_f32_e32 v91, 1.0, v91
	v_mul_f32_e32 v92, v92, v88
	v_mul_f32_e32 v93, v93, v89
	v_mul_f32_e32 v94, v94, v90
	v_mul_f32_e32 v95, v95, v91
	v_bfe_u32 v88, v92, 16, 1
	v_bfe_u32 v89, v93, 16, 1
	v_bfe_u32 v90, v94, 16, 1
	v_bfe_u32 v91, v95, 16, 1
	v_add3_u32 v92, v92, v88, s33
	v_add3_u32 v93, v93, v89, s33
	v_add3_u32 v94, v94, v90, s33
	v_add3_u32 v95, v95, v91, s33
	global_store_short_d16_hi v80, v92, s[24:25] offset:0
	global_store_short_d16_hi v80, v93, s[24:25] offset:32
	global_store_short_d16_hi v80, v94, s[24:25] offset:64
	global_store_short_d16_hi v80, v95, s[24:25] offset:96
	s_branch .Lie_done
.Lie_xb:
	v_lshlrev_b32_e32 v75, 11, v69
	v_lshl_add_u32 v75, v68, 2, v75
	v_mov_b32_e32 v80, v75
	global_store_dword v80, v0, s[26:27] offset:0
	global_store_dword v80, v4, s[26:27] offset:64
	global_store_dword v80, v8, s[26:27] offset:128
	global_store_dword v80, v12, s[26:27] offset:192
	v_add_u32_e32 v81, 0x800, v75
	global_store_dword v81, v1, s[26:27] offset:0
	global_store_dword v81, v5, s[26:27] offset:64
	global_store_dword v81, v9, s[26:27] offset:128
	global_store_dword v81, v13, s[26:27] offset:192
	v_add_u32_e32 v82, 0x1000, v75
	global_store_dword v82, v2, s[26:27] offset:0
	global_store_dword v82, v6, s[26:27] offset:64
	global_store_dword v82, v10, s[26:27] offset:128
	global_store_dword v82, v14, s[26:27] offset:192
	v_add_u32_e32 v83, 0x1800, v75
	global_store_dword v83, v3, s[26:27] offset:0
	global_store_dword v83, v7, s[26:27] offset:64
	global_store_dword v83, v11, s[26:27] offset:128
	global_store_dword v83, v15, s[26:27] offset:192
	v_add_u32_e32 v80, 0x8000, v75
	global_store_dword v80, v16, s[26:27] offset:0
	global_store_dword v80, v20, s[26:27] offset:64
	global_store_dword v80, v24, s[26:27] offset:128
	global_store_dword v80, v28, s[26:27] offset:192
	v_add_u32_e32 v81, 0x8800, v75
	global_store_dword v81, v17, s[26:27] offset:0
	global_store_dword v81, v21, s[26:27] offset:64
	global_store_dword v81, v25, s[26:27] offset:128
	global_store_dword v81, v29, s[26:27] offset:192
	v_add_u32_e32 v82, 0x9000, v75
	global_store_dword v82, v18, s[26:27] offset:0
	global_store_dword v82, v22, s[26:27] offset:64
	global_store_dword v82, v26, s[26:27] offset:128
	global_store_dword v82, v30, s[26:27] offset:192
	v_add_u32_e32 v83, 0x9800, v75
	global_store_dword v83, v19, s[26:27] offset:0
	global_store_dword v83, v23, s[26:27] offset:64
	global_store_dword v83, v27, s[26:27] offset:128
	global_store_dword v83, v31, s[26:27] offset:192
	v_add_u32_e32 v80, 0x10000, v75
	global_store_dword v80, v32, s[26:27] offset:0
	global_store_dword v80, v36, s[26:27] offset:64
	global_store_dword v80, v40, s[26:27] offset:128
	global_store_dword v80, v44, s[26:27] offset:192
	v_add_u32_e32 v81, 0x10800, v75
	global_store_dword v81, v33, s[26:27] offset:0
	global_store_dword v81, v37, s[26:27] offset:64
	global_store_dword v81, v41, s[26:27] offset:128
	global_store_dword v81, v45, s[26:27] offset:192
	v_add_u32_e32 v82, 0x11000, v75
	global_store_dword v82, v34, s[26:27] offset:0
	global_store_dword v82, v38, s[26:27] offset:64
	global_store_dword v82, v42, s[26:27] offset:128
	global_store_dword v82, v46, s[26:27] offset:192
	v_add_u32_e32 v83, 0x11800, v75
	global_store_dword v83, v35, s[26:27] offset:0
	global_store_dword v83, v39, s[26:27] offset:64
	global_store_dword v83, v43, s[26:27] offset:128
	global_store_dword v83, v47, s[26:27] offset:192
	v_add_u32_e32 v80, 0x18000, v75
	global_store_dword v80, v48, s[26:27] offset:0
	global_store_dword v80, v52, s[26:27] offset:64
	global_store_dword v80, v56, s[26:27] offset:128
	global_store_dword v80, v60, s[26:27] offset:192
	v_add_u32_e32 v81, 0x18800, v75
	global_store_dword v81, v49, s[26:27] offset:0
	global_store_dword v81, v53, s[26:27] offset:64
	global_store_dword v81, v57, s[26:27] offset:128
	global_store_dword v81, v61, s[26:27] offset:192
	v_add_u32_e32 v82, 0x19000, v75
	global_store_dword v82, v50, s[26:27] offset:0
	global_store_dword v82, v54, s[26:27] offset:64
	global_store_dword v82, v58, s[26:27] offset:128
	global_store_dword v82, v62, s[26:27] offset:192
	v_add_u32_e32 v83, 0x19800, v75
	global_store_dword v83, v51, s[26:27] offset:0
	global_store_dword v83, v55, s[26:27] offset:64
	global_store_dword v83, v59, s[26:27] offset:128
	global_store_dword v83, v63, s[26:27] offset:192
	s_branch .Lie_done
.Lie_v:
	s_cmpk_ge_u32 s37, 0x1000
	s_cbranch_scc1 .Lie_v_nocache
	v_lshlrev_b32_e32 v75, 11, v69
	v_lshl_add_u32 v75, v68, 2, v75
	v_mov_b32_e32 v80, v75
	global_store_dword v80, v0, s[8:9] offset:0
	global_store_dword v80, v4, s[8:9] offset:64
	global_store_dword v80, v8, s[8:9] offset:128
	global_store_dword v80, v12, s[8:9] offset:192
	v_add_u32_e32 v81, 0x800, v75
	global_store_dword v81, v1, s[8:9] offset:0
	global_store_dword v81, v5, s[8:9] offset:64
	global_store_dword v81, v9, s[8:9] offset:128
	global_store_dword v81, v13, s[8:9] offset:192
	v_add_u32_e32 v82, 0x1000, v75
	global_store_dword v82, v2, s[8:9] offset:0
	global_store_dword v82, v6, s[8:9] offset:64
	global_store_dword v82, v10, s[8:9] offset:128
	global_store_dword v82, v14, s[8:9] offset:192
	v_add_u32_e32 v83, 0x1800, v75
	global_store_dword v83, v3, s[8:9] offset:0
	global_store_dword v83, v7, s[8:9] offset:64
	global_store_dword v83, v11, s[8:9] offset:128
	global_store_dword v83, v15, s[8:9] offset:192
	v_add_u32_e32 v80, 0x8000, v75
	global_store_dword v80, v16, s[8:9] offset:0
	global_store_dword v80, v20, s[8:9] offset:64
	global_store_dword v80, v24, s[8:9] offset:128
	global_store_dword v80, v28, s[8:9] offset:192
	v_add_u32_e32 v81, 0x8800, v75
	global_store_dword v81, v17, s[8:9] offset:0
	global_store_dword v81, v21, s[8:9] offset:64
	global_store_dword v81, v25, s[8:9] offset:128
	global_store_dword v81, v29, s[8:9] offset:192
	v_add_u32_e32 v82, 0x9000, v75
	global_store_dword v82, v18, s[8:9] offset:0
	global_store_dword v82, v22, s[8:9] offset:64
	global_store_dword v82, v26, s[8:9] offset:128
	global_store_dword v82, v30, s[8:9] offset:192
	v_add_u32_e32 v83, 0x9800, v75
	global_store_dword v83, v19, s[8:9] offset:0
	global_store_dword v83, v23, s[8:9] offset:64
	global_store_dword v83, v27, s[8:9] offset:128
	global_store_dword v83, v31, s[8:9] offset:192
	v_add_u32_e32 v80, 0x10000, v75
	global_store_dword v80, v32, s[8:9] offset:0
	global_store_dword v80, v36, s[8:9] offset:64
	global_store_dword v80, v40, s[8:9] offset:128
	global_store_dword v80, v44, s[8:9] offset:192
	v_add_u32_e32 v81, 0x10800, v75
	global_store_dword v81, v33, s[8:9] offset:0
	global_store_dword v81, v37, s[8:9] offset:64
	global_store_dword v81, v41, s[8:9] offset:128
	global_store_dword v81, v45, s[8:9] offset:192
	v_add_u32_e32 v82, 0x11000, v75
	global_store_dword v82, v34, s[8:9] offset:0
	global_store_dword v82, v38, s[8:9] offset:64
	global_store_dword v82, v42, s[8:9] offset:128
	global_store_dword v82, v46, s[8:9] offset:192
	v_add_u32_e32 v83, 0x11800, v75
	global_store_dword v83, v35, s[8:9] offset:0
	global_store_dword v83, v39, s[8:9] offset:64
	global_store_dword v83, v43, s[8:9] offset:128
	global_store_dword v83, v47, s[8:9] offset:192
	v_add_u32_e32 v80, 0x18000, v75
	global_store_dword v80, v48, s[8:9] offset:0
	global_store_dword v80, v52, s[8:9] offset:64
	global_store_dword v80, v56, s[8:9] offset:128
	global_store_dword v80, v60, s[8:9] offset:192
	v_add_u32_e32 v81, 0x18800, v75
	global_store_dword v81, v49, s[8:9] offset:0
	global_store_dword v81, v53, s[8:9] offset:64
	global_store_dword v81, v57, s[8:9] offset:128
	global_store_dword v81, v61, s[8:9] offset:192
	v_add_u32_e32 v82, 0x19000, v75
	global_store_dword v82, v50, s[8:9] offset:0
	global_store_dword v82, v54, s[8:9] offset:64
	global_store_dword v82, v58, s[8:9] offset:128
	global_store_dword v82, v62, s[8:9] offset:192
	v_add_u32_e32 v83, 0x19800, v75
	global_store_dword v83, v51, s[8:9] offset:0
	global_store_dword v83, v55, s[8:9] offset:64
	global_store_dword v83, v59, s[8:9] offset:128
	global_store_dword v83, v63, s[8:9] offset:192

.Lie_qk:
	s_cmp_eq_u32 s1, 0
	s_cselect_b32 s4, s12, s14
	s_cselect_b32 s5, s13, s15
	s_cselect_b32 s6, 0x3e000000, 1.0
	s_mov_b32 s0, 0x9bf6000
	s_cselect_b32 s0, 0x95f6000, s0
	s_add_u32 s34, s10, s0
	s_addc_u32 s35, s11, 0
	v_lshlrev_b32_e32 v88, 2, v64
	global_load_dword v70, v88, s[4:5] offset:0
	global_load_dword v71, v88, s[4:5] offset:64
	global_load_dword v72, v88, s[4:5] offset:128
	global_load_dword v73, v88, s[4:5] offset:192
	v_lshlrev_b32_e32 v74, 10, v69
	v_lshl_add_u32 v74, v68, 1, v74
	v_lshlrev_b32_e32 v75, 11, v69
	v_lshl_add_u32 v75, v68, 2, v75
	v_mov_b32_e32 v96, 0x3c800000
	s_cmp_eq_u32 s1, 1
	s_cselect_b32 s0, 1, 0
	s_cmpk_lt_u32 s37, 0x1000
	s_cselect_b32 s0, s0, 0
	s_waitcnt vmcnt(0)
	v_mul_f32_e32 v76, v0, v0
	v_mul_f32_e32 v77, v1, v1
	v_mul_f32_e32 v78, v2, v2
	v_mul_f32_e32 v79, v3, v3
	v_fmac_f32_e32 v76, v4, v4
	v_fmac_f32_e32 v77, v5, v5
	v_fmac_f32_e32 v78, v6, v6
	v_fmac_f32_e32 v79, v7, v7
	v_fmac_f32_e32 v76, v8, v8
	v_fmac_f32_e32 v77, v9, v9
	v_fmac_f32_e32 v78, v10, v10
	v_fmac_f32_e32 v79, v11, v11
	v_fmac_f32_e32 v76, v12, v12
	v_fmac_f32_e32 v77, v13, v13
	v_fmac_f32_e32 v78, v14, v14
	v_fmac_f32_e32 v79, v15, v15
	v_add_f32_dpp v76, v76, v76 row_ror:8 row_mask:0xf bank_mask:0xf
	v_add_f32_dpp v77, v77, v77 row_ror:8 row_mask:0xf bank_mask:0xf
	v_add_f32_dpp v78, v78, v78 row_ror:8 row_mask:0xf bank_mask:0xf
	v_add_f32_dpp v79, v79, v79 row_ror:8 row_mask:0xf bank_mask:0xf
	v_add_f32_dpp v76, v76, v76 row_ror:4 row_mask:0xf bank_mask:0xf
	v_add_f32_dpp v77, v77, v77 row_ror:4 row_mask:0xf bank_mask:0xf
	v_add_f32_dpp v78, v78, v78 row_ror:4 row_mask:0xf bank_mask:0xf
	v_add_f32_dpp v79, v79, v79 row_ror:4 row_mask:0xf bank_mask:0xf
	v_add_f32_dpp v76, v76, v76 quad_perm:[2,3,0,1] row_mask:0xf bank_mask:0xf
	v_add_f32_dpp v77, v77, v77 quad_perm:[2,3,0,1] row_mask:0xf bank_mask:0xf
	v_add_f32_dpp v78, v78, v78 quad_perm:[2,3,0,1] row_mask:0xf bank_mask:0xf
	v_add_f32_dpp v79, v79, v79 quad_perm:[2,3,0,1] row_mask:0xf bank_mask:0xf
	v_add_f32_dpp v76, v76, v76 quad_perm:[1,0,3,2] row_mask:0xf bank_mask:0xf
	v_add_f32_dpp v77, v77, v77 quad_perm:[1,0,3,2] row_mask:0xf bank_mask:0xf
	v_add_f32_dpp v78, v78, v78 quad_perm:[1,0,3,2] row_mask:0xf bank_mask:0xf
	v_add_f32_dpp v79, v79, v79 quad_perm:[1,0,3,2] row_mask:0xf bank_mask:0xf
	v_fmaak_f32 v76, v96, v76, 0x358637bd
	v_fmaak_f32 v77, v96, v77, 0x358637bd
	v_fmaak_f32 v78, v96, v78, 0x358637bd
	v_fmaak_f32 v79, v96, v79, 0x358637bd
	v_rsq_f32_e32 v76, v76
	v_rsq_f32_e32 v77, v77
	v_rsq_f32_e32 v78, v78
	v_rsq_f32_e32 v79, v79
	v_mov_b32_e32 v80, v74
	v_add_u32_e32 v81, 0x400, v74
	v_add_u32_e32 v82, 0x800, v74
	v_add_u32_e32 v83, 0xc00, v74
	v_mul_f32_e32 v76, s6, v76
	v_mul_f32_e32 v77, s6, v77
	v_mul_f32_e32 v78, s6, v78
	v_mul_f32_e32 v79, s6, v79
	v_mul_f32_e32 v0, v0, v76
	v_mul_f32_e32 v4, v4, v76
	v_mul_f32_e32 v8, v8, v76
	v_mul_f32_e32 v12, v12, v76
	v_mul_f32_e32 v1, v1, v77
	v_mul_f32_e32 v5, v5, v77
	v_mul_f32_e32 v9, v9, v77
	v_mul_f32_e32 v13, v13, v77
	v_mul_f32_e32 v2, v2, v78
	v_mul_f32_e32 v6, v6, v78
	v_mul_f32_e32 v10, v10, v78
	v_mul_f32_e32 v14, v14, v78
	v_mul_f32_e32 v3, v3, v79
	v_mul_f32_e32 v7, v7, v79
	v_mul_f32_e32 v11, v11, v79
	v_mul_f32_e32 v15, v15, v79
	v_mul_f32_e32 v0, v0, v70
	v_mul_f32_e32 v4, v4, v71
	v_mul_f32_e32 v8, v8, v72
	v_mul_f32_e32 v12, v12, v73
	v_mul_f32_e32 v1, v1, v70
	v_mul_f32_e32 v5, v5, v71
	v_mul_f32_e32 v9, v9, v72
	v_mul_f32_e32 v13, v13, v73
	v_mul_f32_e32 v2, v2, v70
	v_mul_f32_e32 v6, v6, v71
	v_mul_f32_e32 v10, v10, v72
	v_mul_f32_e32 v14, v14, v73
	v_mul_f32_e32 v3, v3, v70
	v_mul_f32_e32 v7, v7, v71
	v_mul_f32_e32 v11, v11, v72
	v_mul_f32_e32 v15, v15, v73
	s_cmp_eq_u32 s0, 0
	s_cbranch_scc1 .Lie_nokc_0
	v_mov_b32_e32 v84, v75
	v_add_u32_e32 v85, 0x800, v75
	v_add_u32_e32 v86, 0x1000, v75
	v_add_u32_e32 v87, 0x1800, v75
	global_store_dword v84, v0, s[28:29] offset:0
	global_store_dword v84, v4, s[28:29] offset:64
	global_store_dword v84, v8, s[28:29] offset:128
	global_store_dword v84, v12, s[28:29] offset:192
	global_store_dword v85, v1, s[28:29] offset:0
	global_store_dword v85, v5, s[28:29] offset:64
	global_store_dword v85, v9, s[28:29] offset:128
	global_store_dword v85, v13, s[28:29] offset:192
	global_store_dword v86, v2, s[28:29] offset:0
	global_store_dword v86, v6, s[28:29] offset:64
	global_store_dword v86, v10, s[28:29] offset:128
	global_store_dword v86, v14, s[28:29] offset:192
	global_store_dword v87, v3, s[28:29] offset:0
	global_store_dword v87, v7, s[28:29] offset:64
	global_store_dword v87, v11, s[28:29] offset:128
	global_store_dword v87, v15, s[28:29] offset:192
.Lie_nokc_0:
	v_bfe_u32 v88, v0, 16, 1
	v_bfe_u32 v89, v4, 16, 1
	v_bfe_u32 v90, v8, 16, 1
	v_bfe_u32 v91, v12, 16, 1
	v_add3_u32 v0, v0, v88, s33
	v_add3_u32 v4, v4, v89, s33
	v_add3_u32 v8, v8, v90, s33
	v_add3_u32 v12, v12, v91, s33
	v_bfe_u32 v88, v1, 16, 1
	v_bfe_u32 v89, v5, 16, 1
	v_bfe_u32 v90, v9, 16, 1
	v_bfe_u32 v91, v13, 16, 1
	v_add3_u32 v1, v1, v88, s33
	v_add3_u32 v5, v5, v89, s33
	v_add3_u32 v9, v9, v90, s33
	v_add3_u32 v13, v13, v91, s33
	v_bfe_u32 v88, v2, 16, 1
	v_bfe_u32 v89, v6, 16, 1
	v_bfe_u32 v90, v10, 16, 1
	v_bfe_u32 v91, v14, 16, 1
	v_add3_u32 v2, v2, v88, s33
	v_add3_u32 v6, v6, v89, s33
	v_add3_u32 v10, v10, v90, s33
	v_add3_u32 v14, v14, v91, s33
	v_bfe_u32 v88, v3, 16, 1
	v_bfe_u32 v89, v7, 16, 1
	v_bfe_u32 v90, v11, 16, 1
	v_bfe_u32 v91, v15, 16, 1
	v_add3_u32 v3, v3, v88, s33
	v_add3_u32 v7, v7, v89, s33
	v_add3_u32 v11, v11, v90, s33
	v_add3_u32 v15, v15, v91, s33
	s_cmp_eq_u32 s1, 0
	s_cbranch_scc0 .Lie_kst_0
	global_store_short_d16_hi v80, v0, s[34:35] offset:0
	global_store_short_d16_hi v80, v4, s[34:35] offset:32
	global_store_short_d16_hi v80, v8, s[34:35] offset:64
	global_store_short_d16_hi v80, v12, s[34:35] offset:96
	global_store_short_d16_hi v81, v1, s[34:35] offset:0
	global_store_short_d16_hi v81, v5, s[34:35] offset:32
	global_store_short_d16_hi v81, v9, s[34:35] offset:64
	global_store_short_d16_hi v81, v13, s[34:35] offset:96
	global_store_short_d16_hi v82, v2, s[34:35] offset:0
	global_store_short_d16_hi v82, v6, s[34:35] offset:32
	global_store_short_d16_hi v82, v10, s[34:35] offset:64
	global_store_short_d16_hi v82, v14, s[34:35] offset:96
	global_store_short_d16_hi v83, v3, s[34:35] offset:0
	global_store_short_d16_hi v83, v7, s[34:35] offset:32
	global_store_short_d16_hi v83, v11, s[34:35] offset:64
	global_store_short_d16_hi v83, v15, s[34:35] offset:96
	s_branch .Lie_qkn_0

.Lie_qkn_0:
	v_mul_f32_e32 v76, v16, v16
	v_mul_f32_e32 v77, v17, v17
	v_mul_f32_e32 v78, v18, v18
	v_mul_f32_e32 v79, v19, v19
	v_fmac_f32_e32 v76, v20, v20
	v_fmac_f32_e32 v77, v21, v21
	v_fmac_f32_e32 v78, v22, v22
	v_fmac_f32_e32 v79, v23, v23
	v_fmac_f32_e32 v76, v24, v24
	v_fmac_f32_e32 v77, v25, v25
	v_fmac_f32_e32 v78, v26, v26
	v_fmac_f32_e32 v79, v27, v27
	v_fmac_f32_e32 v76, v28, v28
	v_fmac_f32_e32 v77, v29, v29
	v_fmac_f32_e32 v78, v30, v30
	v_fmac_f32_e32 v79, v31, v31
	v_add_f32_dpp v76, v76, v76 row_ror:8 row_mask:0xf bank_mask:0xf
	v_add_f32_dpp v77, v77, v77 row_ror:8 row_mask:0xf bank_mask:0xf
	v_add_f32_dpp v78, v78, v78 row_ror:8 row_mask:0xf bank_mask:0xf
	v_add_f32_dpp v79, v79, v79 row_ror:8 row_mask:0xf bank_mask:0xf
	v_add_f32_dpp v76, v76, v76 row_ror:4 row_mask:0xf bank_mask:0xf
	v_add_f32_dpp v77, v77, v77 row_ror:4 row_mask:0xf bank_mask:0xf
	v_add_f32_dpp v78, v78, v78 row_ror:4 row_mask:0xf bank_mask:0xf
	v_add_f32_dpp v79, v79, v79 row_ror:4 row_mask:0xf bank_mask:0xf
	v_add_f32_dpp v76, v76, v76 quad_perm:[2,3,0,1] row_mask:0xf bank_mask:0xf
	v_add_f32_dpp v77, v77, v77 quad_perm:[2,3,0,1] row_mask:0xf bank_mask:0xf
	v_add_f32_dpp v78, v78, v78 quad_perm:[2,3,0,1] row_mask:0xf bank_mask:0xf
	v_add_f32_dpp v79, v79, v79 quad_perm:[2,3,0,1] row_mask:0xf bank_mask:0xf
	v_add_f32_dpp v76, v76, v76 quad_perm:[1,0,3,2] row_mask:0xf bank_mask:0xf
	v_add_f32_dpp v77, v77, v77 quad_perm:[1,0,3,2] row_mask:0xf bank_mask:0xf
	v_add_f32_dpp v78, v78, v78 quad_perm:[1,0,3,2] row_mask:0xf bank_mask:0xf
	v_add_f32_dpp v79, v79, v79 quad_perm:[1,0,3,2] row_mask:0xf bank_mask:0xf
	v_fmaak_f32 v76, v96, v76, 0x358637bd
	v_fmaak_f32 v77, v96, v77, 0x358637bd
	v_fmaak_f32 v78, v96, v78, 0x358637bd
	v_fmaak_f32 v79, v96, v79, 0x358637bd
	v_rsq_f32_e32 v76, v76
	v_rsq_f32_e32 v77, v77
	v_rsq_f32_e32 v78, v78
	v_rsq_f32_e32 v79, v79
	v_add_u32_e32 v80, 0x4000, v74
	v_add_u32_e32 v81, 0x4400, v74
	v_add_u32_e32 v82, 0x4800, v74
	v_add_u32_e32 v83, 0x4c00, v74
	v_mul_f32_e32 v76, s6, v76
	v_mul_f32_e32 v77, s6, v77
	v_mul_f32_e32 v78, s6, v78
	v_mul_f32_e32 v79, s6, v79
	v_mul_f32_e32 v16, v16, v76
	v_mul_f32_e32 v20, v20, v76
	v_mul_f32_e32 v24, v24, v76
	v_mul_f32_e32 v28, v28, v76
	v_mul_f32_e32 v17, v17, v77
	v_mul_f32_e32 v21, v21, v77
	v_mul_f32_e32 v25, v25, v77
	v_mul_f32_e32 v29, v29, v77
	v_mul_f32_e32 v18, v18, v78
	v_mul_f32_e32 v22, v22, v78
	v_mul_f32_e32 v26, v26, v78
	v_mul_f32_e32 v30, v30, v78
	v_mul_f32_e32 v19, v19, v79
	v_mul_f32_e32 v23, v23, v79
	v_mul_f32_e32 v27, v27, v79
	v_mul_f32_e32 v31, v31, v79
	v_mul_f32_e32 v16, v16, v70
	v_mul_f32_e32 v20, v20, v71
	v_mul_f32_e32 v24, v24, v72
	v_mul_f32_e32 v28, v28, v73
	v_mul_f32_e32 v17, v17, v70
	v_mul_f32_e32 v21, v21, v71
	v_mul_f32_e32 v25, v25, v72
	v_mul_f32_e32 v29, v29, v73
	v_mul_f32_e32 v18, v18, v70
	v_mul_f32_e32 v22, v22, v71
	v_mul_f32_e32 v26, v26, v72
	v_mul_f32_e32 v30, v30, v73
	v_mul_f32_e32 v19, v19, v70
	v_mul_f32_e32 v23, v23, v71
	v_mul_f32_e32 v27, v27, v72
	v_mul_f32_e32 v31, v31, v73
	s_cmp_eq_u32 s0, 0
	s_cbranch_scc1 .Lie_nokc_1
	v_add_u32_e32 v84, 0x8000, v75
	v_add_u32_e32 v85, 0x8800, v75
	v_add_u32_e32 v86, 0x9000, v75
	v_add_u32_e32 v87, 0x9800, v75
	global_store_dword v84, v16, s[28:29] offset:0
	global_store_dword v84, v20, s[28:29] offset:64
	global_store_dword v84, v24, s[28:29] offset:128
	global_store_dword v84, v28, s[28:29] offset:192
	global_store_dword v85, v17, s[28:29] offset:0
	global_store_dword v85, v21, s[28:29] offset:64
	global_store_dword v85, v25, s[28:29] offset:128
	global_store_dword v85, v29, s[28:29] offset:192
	global_store_dword v86, v18, s[28:29] offset:0
	global_store_dword v86, v22, s[28:29] offset:64
	global_store_dword v86, v26, s[28:29] offset:128
	global_store_dword v86, v30, s[28:29] offset:192
	global_store_dword v87, v19, s[28:29] offset:0
	global_store_dword v87, v23, s[28:29] offset:64
	global_store_dword v87, v27, s[28:29] offset:128
	global_store_dword v87, v31, s[28:29] offset:192
.Lie_nokc_1:
	v_bfe_u32 v88, v16, 16, 1
	v_bfe_u32 v89, v20, 16, 1
	v_bfe_u32 v90, v24, 16, 1
	v_bfe_u32 v91, v28, 16, 1
	v_add3_u32 v16, v16, v88, s33
	v_add3_u32 v20, v20, v89, s33
	v_add3_u32 v24, v24, v90, s33
	v_add3_u32 v28, v28, v91, s33
	v_bfe_u32 v88, v17, 16, 1
	v_bfe_u32 v89, v21, 16, 1
	v_bfe_u32 v90, v25, 16, 1
	v_bfe_u32 v91, v29, 16, 1
	v_add3_u32 v17, v17, v88, s33
	v_add3_u32 v21, v21, v89, s33
	v_add3_u32 v25, v25, v90, s33
	v_add3_u32 v29, v29, v91, s33
	v_bfe_u32 v88, v18, 16, 1
	v_bfe_u32 v89, v22, 16, 1
	v_bfe_u32 v90, v26, 16, 1
	v_bfe_u32 v91, v30, 16, 1
	v_add3_u32 v18, v18, v88, s33
	v_add3_u32 v22, v22, v89, s33
	v_add3_u32 v26, v26, v90, s33
	v_add3_u32 v30, v30, v91, s33
	v_bfe_u32 v88, v19, 16, 1
	v_bfe_u32 v89, v23, 16, 1
	v_bfe_u32 v90, v27, 16, 1
	v_bfe_u32 v91, v31, 16, 1
	v_add3_u32 v19, v19, v88, s33
	v_add3_u32 v23, v23, v89, s33
	v_add3_u32 v27, v27, v90, s33
	v_add3_u32 v31, v31, v91, s33
	s_cmp_eq_u32 s1, 0
	s_cbranch_scc0 .Lie_kst_1
	global_store_short_d16_hi v80, v16, s[34:35] offset:0
	global_store_short_d16_hi v80, v20, s[34:35] offset:32
	global_store_short_d16_hi v80, v24, s[34:35] offset:64
	global_store_short_d16_hi v80, v28, s[34:35] offset:96
	global_store_short_d16_hi v81, v17, s[34:35] offset:0
	global_store_short_d16_hi v81, v21, s[34:35] offset:32
	global_store_short_d16_hi v81, v25, s[34:35] offset:64
	global_store_short_d16_hi v81, v29, s[34:35] offset:96
	global_store_short_d16_hi v82, v18, s[34:35] offset:0
	global_store_short_d16_hi v82, v22, s[34:35] offset:32
	global_store_short_d16_hi v82, v26, s[34:35] offset:64
	global_store_short_d16_hi v82, v30, s[34:35] offset:96
	global_store_short_d16_hi v83, v19, s[34:35] offset:0
	global_store_short_d16_hi v83, v23, s[34:35] offset:32
	global_store_short_d16_hi v83, v27, s[34:35] offset:64
	global_store_short_d16_hi v83, v31, s[34:35] offset:96
	s_branch .Lie_qkn_1

.Lie_qkn_1:
	v_mul_f32_e32 v76, v32, v32
	v_mul_f32_e32 v77, v33, v33
	v_mul_f32_e32 v78, v34, v34
	v_mul_f32_e32 v79, v35, v35
	v_fmac_f32_e32 v76, v36, v36
	v_fmac_f32_e32 v77, v37, v37
	v_fmac_f32_e32 v78, v38, v38
	v_fmac_f32_e32 v79, v39, v39
	v_fmac_f32_e32 v76, v40, v40
	v_fmac_f32_e32 v77, v41, v41
	v_fmac_f32_e32 v78, v42, v42
	v_fmac_f32_e32 v79, v43, v43
	v_fmac_f32_e32 v76, v44, v44
	v_fmac_f32_e32 v77, v45, v45
	v_fmac_f32_e32 v78, v46, v46
	v_fmac_f32_e32 v79, v47, v47
	v_add_f32_dpp v76, v76, v76 row_ror:8 row_mask:0xf bank_mask:0xf
	v_add_f32_dpp v77, v77, v77 row_ror:8 row_mask:0xf bank_mask:0xf
	v_add_f32_dpp v78, v78, v78 row_ror:8 row_mask:0xf bank_mask:0xf
	v_add_f32_dpp v79, v79, v79 row_ror:8 row_mask:0xf bank_mask:0xf
	v_add_f32_dpp v76, v76, v76 row_ror:4 row_mask:0xf bank_mask:0xf
	v_add_f32_dpp v77, v77, v77 row_ror:4 row_mask:0xf bank_mask:0xf
	v_add_f32_dpp v78, v78, v78 row_ror:4 row_mask:0xf bank_mask:0xf
	v_add_f32_dpp v79, v79, v79 row_ror:4 row_mask:0xf bank_mask:0xf
	v_add_f32_dpp v76, v76, v76 quad_perm:[2,3,0,1] row_mask:0xf bank_mask:0xf
	v_add_f32_dpp v77, v77, v77 quad_perm:[2,3,0,1] row_mask:0xf bank_mask:0xf
	v_add_f32_dpp v78, v78, v78 quad_perm:[2,3,0,1] row_mask:0xf bank_mask:0xf
	v_add_f32_dpp v79, v79, v79 quad_perm:[2,3,0,1] row_mask:0xf bank_mask:0xf
	v_add_f32_dpp v76, v76, v76 quad_perm:[1,0,3,2] row_mask:0xf bank_mask:0xf
	v_add_f32_dpp v77, v77, v77 quad_perm:[1,0,3,2] row_mask:0xf bank_mask:0xf
	v_add_f32_dpp v78, v78, v78 quad_perm:[1,0,3,2] row_mask:0xf bank_mask:0xf
	v_add_f32_dpp v79, v79, v79 quad_perm:[1,0,3,2] row_mask:0xf bank_mask:0xf
	v_fmaak_f32 v76, v96, v76, 0x358637bd
	v_fmaak_f32 v77, v96, v77, 0x358637bd
	v_fmaak_f32 v78, v96, v78, 0x358637bd
	v_fmaak_f32 v79, v96, v79, 0x358637bd
	v_rsq_f32_e32 v76, v76
	v_rsq_f32_e32 v77, v77
	v_rsq_f32_e32 v78, v78
	v_rsq_f32_e32 v79, v79
	v_add_u32_e32 v80, 0x8000, v74
	v_add_u32_e32 v81, 0x8400, v74
	v_add_u32_e32 v82, 0x8800, v74
	v_add_u32_e32 v83, 0x8c00, v74
	v_mul_f32_e32 v76, s6, v76
	v_mul_f32_e32 v77, s6, v77
	v_mul_f32_e32 v78, s6, v78
	v_mul_f32_e32 v79, s6, v79
	v_mul_f32_e32 v32, v32, v76
	v_mul_f32_e32 v36, v36, v76
	v_mul_f32_e32 v40, v40, v76
	v_mul_f32_e32 v44, v44, v76
	v_mul_f32_e32 v33, v33, v77
	v_mul_f32_e32 v37, v37, v77
	v_mul_f32_e32 v41, v41, v77
	v_mul_f32_e32 v45, v45, v77
	v_mul_f32_e32 v34, v34, v78
	v_mul_f32_e32 v38, v38, v78
	v_mul_f32_e32 v42, v42, v78
	v_mul_f32_e32 v46, v46, v78
	v_mul_f32_e32 v35, v35, v79
	v_mul_f32_e32 v39, v39, v79
	v_mul_f32_e32 v43, v43, v79
	v_mul_f32_e32 v47, v47, v79
	v_mul_f32_e32 v32, v32, v70
	v_mul_f32_e32 v36, v36, v71
	v_mul_f32_e32 v40, v40, v72
	v_mul_f32_e32 v44, v44, v73
	v_mul_f32_e32 v33, v33, v70
	v_mul_f32_e32 v37, v37, v71
	v_mul_f32_e32 v41, v41, v72
	v_mul_f32_e32 v45, v45, v73
	v_mul_f32_e32 v34, v34, v70
	v_mul_f32_e32 v38, v38, v71
	v_mul_f32_e32 v42, v42, v72
	v_mul_f32_e32 v46, v46, v73
	v_mul_f32_e32 v35, v35, v70
	v_mul_f32_e32 v39, v39, v71
	v_mul_f32_e32 v43, v43, v72
	v_mul_f32_e32 v47, v47, v73
	s_cmp_eq_u32 s0, 0
	s_cbranch_scc1 .Lie_nokc_2
	v_add_u32_e32 v84, 0x10000, v75
	v_add_u32_e32 v85, 0x10800, v75
	v_add_u32_e32 v86, 0x11000, v75
	v_add_u32_e32 v87, 0x11800, v75
	global_store_dword v84, v32, s[28:29] offset:0
	global_store_dword v84, v36, s[28:29] offset:64
	global_store_dword v84, v40, s[28:29] offset:128
	global_store_dword v84, v44, s[28:29] offset:192
	global_store_dword v85, v33, s[28:29] offset:0
	global_store_dword v85, v37, s[28:29] offset:64
	global_store_dword v85, v41, s[28:29] offset:128
	global_store_dword v85, v45, s[28:29] offset:192
	global_store_dword v86, v34, s[28:29] offset:0
	global_store_dword v86, v38, s[28:29] offset:64
	global_store_dword v86, v42, s[28:29] offset:128
	global_store_dword v86, v46, s[28:29] offset:192
	global_store_dword v87, v35, s[28:29] offset:0
	global_store_dword v87, v39, s[28:29] offset:64
	global_store_dword v87, v43, s[28:29] offset:128
	global_store_dword v87, v47, s[28:29] offset:192
.Lie_nokc_2:
	v_bfe_u32 v88, v32, 16, 1
	v_bfe_u32 v89, v36, 16, 1
	v_bfe_u32 v90, v40, 16, 1
	v_bfe_u32 v91, v44, 16, 1
	v_add3_u32 v32, v32, v88, s33
	v_add3_u32 v36, v36, v89, s33
	v_add3_u32 v40, v40, v90, s33
	v_add3_u32 v44, v44, v91, s33
	v_bfe_u32 v88, v33, 16, 1
	v_bfe_u32 v89, v37, 16, 1
	v_bfe_u32 v90, v41, 16, 1
	v_bfe_u32 v91, v45, 16, 1
	v_add3_u32 v33, v33, v88, s33
	v_add3_u32 v37, v37, v89, s33
	v_add3_u32 v41, v41, v90, s33
	v_add3_u32 v45, v45, v91, s33
	v_bfe_u32 v88, v34, 16, 1
	v_bfe_u32 v89, v38, 16, 1
	v_bfe_u32 v90, v42, 16, 1
	v_bfe_u32 v91, v46, 16, 1
	v_add3_u32 v34, v34, v88, s33
	v_add3_u32 v38, v38, v89, s33
	v_add3_u32 v42, v42, v90, s33
	v_add3_u32 v46, v46, v91, s33
	v_bfe_u32 v88, v35, 16, 1
	v_bfe_u32 v89, v39, 16, 1
	v_bfe_u32 v90, v43, 16, 1
	v_bfe_u32 v91, v47, 16, 1
	v_add3_u32 v35, v35, v88, s33
	v_add3_u32 v39, v39, v89, s33
	v_add3_u32 v43, v43, v90, s33
	v_add3_u32 v47, v47, v91, s33
	s_cmp_eq_u32 s1, 0
	s_cbranch_scc0 .Lie_kst_2
	global_store_short_d16_hi v80, v32, s[34:35] offset:0
	global_store_short_d16_hi v80, v36, s[34:35] offset:32
	global_store_short_d16_hi v80, v40, s[34:35] offset:64
	global_store_short_d16_hi v80, v44, s[34:35] offset:96
	global_store_short_d16_hi v81, v33, s[34:35] offset:0
	global_store_short_d16_hi v81, v37, s[34:35] offset:32
	global_store_short_d16_hi v81, v41, s[34:35] offset:64
	global_store_short_d16_hi v81, v45, s[34:35] offset:96
	global_store_short_d16_hi v82, v34, s[34:35] offset:0
	global_store_short_d16_hi v82, v38, s[34:35] offset:32
	global_store_short_d16_hi v82, v42, s[34:35] offset:64
	global_store_short_d16_hi v82, v46, s[34:35] offset:96
	global_store_short_d16_hi v83, v35, s[34:35] offset:0
	global_store_short_d16_hi v83, v39, s[34:35] offset:32
	global_store_short_d16_hi v83, v43, s[34:35] offset:64
	global_store_short_d16_hi v83, v47, s[34:35] offset:96
	s_branch .Lie_qkn_2

.Lie_qkn_2:
	v_mul_f32_e32 v76, v48, v48
	v_mul_f32_e32 v77, v49, v49
	v_mul_f32_e32 v78, v50, v50
	v_mul_f32_e32 v79, v51, v51
	v_fmac_f32_e32 v76, v52, v52
	v_fmac_f32_e32 v77, v53, v53
	v_fmac_f32_e32 v78, v54, v54
	v_fmac_f32_e32 v79, v55, v55
	v_fmac_f32_e32 v76, v56, v56
	v_fmac_f32_e32 v77, v57, v57
	v_fmac_f32_e32 v78, v58, v58
	v_fmac_f32_e32 v79, v59, v59
	v_fmac_f32_e32 v76, v60, v60
	v_fmac_f32_e32 v77, v61, v61
	v_fmac_f32_e32 v78, v62, v62
	v_fmac_f32_e32 v79, v63, v63
	v_add_f32_dpp v76, v76, v76 row_ror:8 row_mask:0xf bank_mask:0xf
	v_add_f32_dpp v77, v77, v77 row_ror:8 row_mask:0xf bank_mask:0xf
	v_add_f32_dpp v78, v78, v78 row_ror:8 row_mask:0xf bank_mask:0xf
	v_add_f32_dpp v79, v79, v79 row_ror:8 row_mask:0xf bank_mask:0xf
	v_add_f32_dpp v76, v76, v76 row_ror:4 row_mask:0xf bank_mask:0xf
	v_add_f32_dpp v77, v77, v77 row_ror:4 row_mask:0xf bank_mask:0xf
	v_add_f32_dpp v78, v78, v78 row_ror:4 row_mask:0xf bank_mask:0xf
	v_add_f32_dpp v79, v79, v79 row_ror:4 row_mask:0xf bank_mask:0xf
	v_add_f32_dpp v76, v76, v76 quad_perm:[2,3,0,1] row_mask:0xf bank_mask:0xf
	v_add_f32_dpp v77, v77, v77 quad_perm:[2,3,0,1] row_mask:0xf bank_mask:0xf
	v_add_f32_dpp v78, v78, v78 quad_perm:[2,3,0,1] row_mask:0xf bank_mask:0xf
	v_add_f32_dpp v79, v79, v79 quad_perm:[2,3,0,1] row_mask:0xf bank_mask:0xf
	v_add_f32_dpp v76, v76, v76 quad_perm:[1,0,3,2] row_mask:0xf bank_mask:0xf
	v_add_f32_dpp v77, v77, v77 quad_perm:[1,0,3,2] row_mask:0xf bank_mask:0xf
	v_add_f32_dpp v78, v78, v78 quad_perm:[1,0,3,2] row_mask:0xf bank_mask:0xf
	v_add_f32_dpp v79, v79, v79 quad_perm:[1,0,3,2] row_mask:0xf bank_mask:0xf
	v_fmaak_f32 v76, v96, v76, 0x358637bd
	v_fmaak_f32 v77, v96, v77, 0x358637bd
	v_fmaak_f32 v78, v96, v78, 0x358637bd
	v_fmaak_f32 v79, v96, v79, 0x358637bd
	v_rsq_f32_e32 v76, v76
	v_rsq_f32_e32 v77, v77
	v_rsq_f32_e32 v78, v78
	v_rsq_f32_e32 v79, v79
	v_add_u32_e32 v80, 0xc000, v74
	v_add_u32_e32 v81, 0xc400, v74
	v_add_u32_e32 v82, 0xc800, v74
	v_add_u32_e32 v83, 0xcc00, v74
	v_mul_f32_e32 v76, s6, v76
	v_mul_f32_e32 v77, s6, v77
	v_mul_f32_e32 v78, s6, v78
	v_mul_f32_e32 v79, s6, v79
	v_mul_f32_e32 v48, v48, v76
	v_mul_f32_e32 v52, v52, v76
	v_mul_f32_e32 v56, v56, v76
	v_mul_f32_e32 v60, v60, v76
	v_mul_f32_e32 v49, v49, v77
	v_mul_f32_e32 v53, v53, v77
	v_mul_f32_e32 v57, v57, v77
	v_mul_f32_e32 v61, v61, v77
	v_mul_f32_e32 v50, v50, v78
	v_mul_f32_e32 v54, v54, v78
	v_mul_f32_e32 v58, v58, v78
	v_mul_f32_e32 v62, v62, v78
	v_mul_f32_e32 v51, v51, v79
	v_mul_f32_e32 v55, v55, v79
	v_mul_f32_e32 v59, v59, v79
	v_mul_f32_e32 v63, v63, v79
	v_mul_f32_e32 v48, v48, v70
	v_mul_f32_e32 v52, v52, v71
	v_mul_f32_e32 v56, v56, v72
	v_mul_f32_e32 v60, v60, v73
	v_mul_f32_e32 v49, v49, v70
	v_mul_f32_e32 v53, v53, v71
	v_mul_f32_e32 v57, v57, v72
	v_mul_f32_e32 v61, v61, v73
	v_mul_f32_e32 v50, v50, v70
	v_mul_f32_e32 v54, v54, v71
	v_mul_f32_e32 v58, v58, v72
	v_mul_f32_e32 v62, v62, v73
	v_mul_f32_e32 v51, v51, v70
	v_mul_f32_e32 v55, v55, v71
	v_mul_f32_e32 v59, v59, v72
	v_mul_f32_e32 v63, v63, v73
	s_cmp_eq_u32 s0, 0
	s_cbranch_scc1 .Lie_nokc_3
	v_add_u32_e32 v84, 0x18000, v75
	v_add_u32_e32 v85, 0x18800, v75
	v_add_u32_e32 v86, 0x19000, v75
	v_add_u32_e32 v87, 0x19800, v75
	global_store_dword v84, v48, s[28:29] offset:0
	global_store_dword v84, v52, s[28:29] offset:64
	global_store_dword v84, v56, s[28:29] offset:128
	global_store_dword v84, v60, s[28:29] offset:192
	global_store_dword v85, v49, s[28:29] offset:0
	global_store_dword v85, v53, s[28:29] offset:64
	global_store_dword v85, v57, s[28:29] offset:128
	global_store_dword v85, v61, s[28:29] offset:192
	global_store_dword v86, v50, s[28:29] offset:0
	global_store_dword v86, v54, s[28:29] offset:64
	global_store_dword v86, v58, s[28:29] offset:128
	global_store_dword v86, v62, s[28:29] offset:192
	global_store_dword v87, v51, s[28:29] offset:0
	global_store_dword v87, v55, s[28:29] offset:64
	global_store_dword v87, v59, s[28:29] offset:128
	global_store_dword v87, v63, s[28:29] offset:192
.Lie_nokc_3:
	v_bfe_u32 v88, v48, 16, 1
	v_bfe_u32 v89, v52, 16, 1
	v_bfe_u32 v90, v56, 16, 1
	v_bfe_u32 v91, v60, 16, 1
	v_add3_u32 v48, v48, v88, s33
	v_add3_u32 v52, v52, v89, s33
	v_add3_u32 v56, v56, v90, s33
	v_add3_u32 v60, v60, v91, s33
	v_bfe_u32 v88, v49, 16, 1
	v_bfe_u32 v89, v53, 16, 1
	v_bfe_u32 v90, v57, 16, 1
	v_bfe_u32 v91, v61, 16, 1
	v_add3_u32 v49, v49, v88, s33
	v_add3_u32 v53, v53, v89, s33
	v_add3_u32 v57, v57, v90, s33
	v_add3_u32 v61, v61, v91, s33
	v_bfe_u32 v88, v50, 16, 1
	v_bfe_u32 v89, v54, 16, 1
	v_bfe_u32 v90, v58, 16, 1
	v_bfe_u32 v91, v62, 16, 1
	v_add3_u32 v50, v50, v88, s33
	v_add3_u32 v54, v54, v89, s33
	v_add3_u32 v58, v58, v90, s33
	v_add3_u32 v62, v62, v91, s33
	v_bfe_u32 v88, v51, 16, 1
	v_bfe_u32 v89, v55, 16, 1
	v_bfe_u32 v90, v59, 16, 1
	v_bfe_u32 v91, v63, 16, 1
	v_add3_u32 v51, v51, v88, s33
	v_add3_u32 v55, v55, v89, s33
	v_add3_u32 v59, v59, v90, s33
	v_add3_u32 v63, v63, v91, s33
	s_cmp_eq_u32 s1, 0
	s_cbranch_scc0 .Lie_kst_3
	global_store_short_d16_hi v80, v48, s[34:35] offset:0
	global_store_short_d16_hi v80, v52, s[34:35] offset:32
	global_store_short_d16_hi v80, v56, s[34:35] offset:64
	global_store_short_d16_hi v80, v60, s[34:35] offset:96
	global_store_short_d16_hi v81, v49, s[34:35] offset:0
	global_store_short_d16_hi v81, v53, s[34:35] offset:32
	global_store_short_d16_hi v81, v57, s[34:35] offset:64
	global_store_short_d16_hi v81, v61, s[34:35] offset:96
	global_store_short_d16_hi v82, v50, s[34:35] offset:0
	global_store_short_d16_hi v82, v54, s[34:35] offset:32
	global_store_short_d16_hi v82, v58, s[34:35] offset:64
	global_store_short_d16_hi v82, v62, s[34:35] offset:96
	global_store_short_d16_hi v83, v51, s[34:35] offset:0
	global_store_short_d16_hi v83, v55, s[34:35] offset:32
	global_store_short_d16_hi v83, v59, s[34:35] offset:64
	global_store_short_d16_hi v83, v63, s[34:35] offset:96
	s_branch .Lie_qkn_3
